# non-leader workgroups poll the cross-XCC release word directly (one hop fewer); nontemporal stores in the hand-written conv / gMLP epilogues
# speedup vs baseline: 1.0024x; 1.0024x over previous
.LBB0_91:
	s_or_b64 exec, exec, s[8:9]
	v_cvt_f32_u32_e32 v5, v3
	s_waitcnt vmcnt(0)
	v_readfirstlane_b32 s3, v4
	v_sub_u32_e32 v4, 0, v3
	v_rcp_iflag_f32_e32 v5, v5
	v_add_u32_e32 v6, s3, v2
	v_mul_f32_e32 v5, 0x4f7ffffe, v5
	v_cvt_u32_f32_e32 v5, v5
	v_mul_lo_u32 v2, v4, v5
	v_mul_hi_u32 v2, v5, v2
	v_add_u32_e32 v2, v5, v2
	v_mul_hi_u32 v2, v6, v2
	v_mul_lo_u32 v4, v2, v3
	v_sub_u32_e32 v4, v6, v4
	v_add_u32_e32 v5, 1, v2
	v_cmp_ge_u32_e32 vcc, v4, v3
	s_nop 1
	v_cndmask_b32_e32 v2, v2, v5, vcc
	v_sub_u32_e32 v5, v4, v3
	v_cndmask_b32_e32 v4, v4, v5, vcc
	v_add_u32_e32 v5, 1, v2
	v_cmp_ge_u32_e32 vcc, v4, v3
	v_add_u32_e32 v4, 1, v6
	s_nop 0
	v_cndmask_b32_e32 v2, v2, v5, vcc
	v_mul_lo_u32 v5, v3, v2
	v_add_u32_e32 v3, v5, v3
	v_cmp_ne_u32_e32 vcc, v4, v3
	s_and_saveexec_b64 s[6:7], vcc
	s_xor_b64 s[6:7], exec, s[6:7]
	s_cbranch_execz .LBB0_105
	s_waitcnt lgkmcnt(0)
	v_mov_b32_e32 v1, 0x83500
	global_load_dword v1, v1, s[64:65] sc1
	s_add_u32 s20, s64, 0x83500
	s_addc_u32 s21, s65, 0
	s_waitcnt vmcnt(0)
	v_cmp_eq_u32_e32 vcc, v1, v2
	s_and_saveexec_b64 s[8:9], vcc
	s_cbranch_execz .LBB0_104
	s_add_u32 s10, s64, 0x80200
	s_addc_u32 s11, s65, 0
	s_mov_b32 s3, 1
	s_mov_b64 s[22:23], 0
	v_mov_b32_e32 v1, 0
	s_branch .LBB0_95

.LBB0_427:
	s_or_b64 exec, exec, s[8:9]
	v_cvt_f32_u32_e32 v4, v2
	s_waitcnt vmcnt(0)
	v_readfirstlane_b32 s6, v3
	v_sub_u32_e32 v3, 0, v2
	v_rcp_iflag_f32_e32 v4, v4
	v_add_u32_e32 v5, s6, v1
	v_mul_f32_e32 v4, 0x4f7ffffe, v4
	v_cvt_u32_f32_e32 v4, v4
	v_mul_lo_u32 v1, v3, v4
	v_mul_hi_u32 v1, v4, v1
	v_add_u32_e32 v1, v4, v1
	v_mul_hi_u32 v1, v5, v1
	v_mul_lo_u32 v3, v1, v2
	v_sub_u32_e32 v3, v5, v3
	v_add_u32_e32 v4, 1, v1
	v_cmp_ge_u32_e32 vcc, v3, v2
	s_nop 1
	v_cndmask_b32_e32 v1, v1, v4, vcc
	v_sub_u32_e32 v4, v3, v2
	v_cndmask_b32_e32 v3, v3, v4, vcc
	v_add_u32_e32 v4, 1, v1
	v_cmp_ge_u32_e32 vcc, v3, v2
	v_add_u32_e32 v3, 1, v5
	s_nop 0
	v_cndmask_b32_e32 v1, v1, v4, vcc
	v_mul_lo_u32 v4, v2, v1
	v_add_u32_e32 v2, v4, v2
	v_cmp_ne_u32_e32 vcc, v3, v2
	s_and_saveexec_b64 s[6:7], vcc
	s_xor_b64 s[6:7], exec, s[6:7]
	s_cbranch_execz .LBB0_441
	s_waitcnt lgkmcnt(0)
	v_mov_b32_e32 v0, 0x83500
	global_load_dword v0, v0, s[64:65] sc1
	s_add_u32 s12, s64, 0x83500
	s_addc_u32 s13, s65, 0
	s_waitcnt vmcnt(0)
	v_cmp_eq_u32_e32 vcc, v0, v1
	s_and_saveexec_b64 s[8:9], vcc
	s_cbranch_execz .LBB0_440
	s_add_u32 s10, s64, 0x80200
	s_addc_u32 s11, s65, 0
	s_mov_b32 s24, 1
	s_mov_b64 s[14:15], 0
	v_mov_b32_e32 v0, 0
	s_branch .LBB0_431

.Lcv_fd1:
.Lcv_nofetch:
	v_mov_b32_e32 v80, v78
	v_mov_b32_e32 v81, v79
	v_mov_b32_e32 v82, v78
	v_mov_b32_e32 v83, v79
	v_mov_b32_e32 v84, v78
	v_mov_b32_e32 v85, v79
	v_mov_b32_e32 v86, v78
	v_mov_b32_e32 v87, v79
	v_mov_b32_e32 v88, v78
	v_mov_b32_e32 v89, v79
	v_mov_b32_e32 v90, v78
	v_mov_b32_e32 v91, v79
	v_mov_b32_e32 v92, v78
	v_mov_b32_e32 v93, v79
	v_mov_b32_e32 v94, v78
	v_mov_b32_e32 v95, v79
	v_mov_b32_e32 v96, v78
	v_mov_b32_e32 v97, v79
	v_mov_b32_e32 v98, v78
	v_mov_b32_e32 v99, v79
	v_mov_b32_e32 v100, v78
	v_mov_b32_e32 v101, v79
	v_mov_b32_e32 v102, v78
	v_mov_b32_e32 v103, v79
	v_mov_b32_e32 v104, v78
	v_mov_b32_e32 v105, v79
	v_mov_b32_e32 v106, v78
	v_mov_b32_e32 v107, v79
	v_mov_b32_e32 v108, v78
	v_mov_b32_e32 v109, v79
	v_mov_b32_e32 v110, v78
	v_mov_b32_e32 v111, v79
	ds_read_b32 v144, v2 offset:0
	ds_read_b32 v145, v2 offset:1024
	ds_read_b32 v146, v2 offset:2048
	ds_read_b32 v147, v2 offset:3072
	ds_read_b32 v148, v2 offset:4096
	ds_read_b32 v149, v2 offset:5120
	ds_read_b32 v150, v2 offset:6144
	ds_read_b32 v151, v2 offset:7168
	ds_read_b32 v152, v2 offset:8192
	ds_read_b32 v153, v2 offset:9216
	ds_read_b32 v154, v2 offset:10240
	ds_read_b32 v155, v2 offset:11264
	ds_read_b32 v156, v2 offset:12288
	s_waitcnt lgkmcnt(12)
	v_lshlrev_b32_e32 v204, 16, v144
	v_and_b32_e32 v205, 0xffff0000, v144
	v_pk_fma_f32 v[80:81], v[16:17], v[204:205], v[80:81]
	ds_read_b32 v157, v2 offset:13312
	s_waitcnt lgkmcnt(12)
	v_lshlrev_b32_e32 v204, 16, v145
	v_and_b32_e32 v205, 0xffff0000, v145
	v_pk_fma_f32 v[80:81], v[18:19], v[204:205], v[80:81]
	v_pk_fma_f32 v[82:83], v[16:17], v[204:205], v[82:83]
	ds_read_b32 v158, v2 offset:14336
	s_waitcnt lgkmcnt(12)
	v_lshlrev_b32_e32 v204, 16, v146
	v_and_b32_e32 v205, 0xffff0000, v146
	v_pk_fma_f32 v[80:81], v[20:21], v[204:205], v[80:81]
	v_pk_fma_f32 v[82:83], v[18:19], v[204:205], v[82:83]
	v_pk_fma_f32 v[84:85], v[16:17], v[204:205], v[84:85]
	ds_read_b32 v159, v2 offset:15360
	s_waitcnt lgkmcnt(12)
	v_lshlrev_b32_e32 v204, 16, v147
	v_and_b32_e32 v205, 0xffff0000, v147
	v_pk_fma_f32 v[80:81], v[22:23], v[204:205], v[80:81]
	v_pk_fma_f32 v[82:83], v[20:21], v[204:205], v[82:83]
	v_pk_fma_f32 v[84:85], v[18:19], v[204:205], v[84:85]
	v_pk_fma_f32 v[86:87], v[16:17], v[204:205], v[86:87]
	ds_read_b32 v160, v2 offset:16384
	s_waitcnt lgkmcnt(12)
	v_lshlrev_b32_e32 v204, 16, v148
	v_and_b32_e32 v205, 0xffff0000, v148
	v_pk_fma_f32 v[80:81], v[24:25], v[204:205], v[80:81]
	v_pk_fma_f32 v[82:83], v[22:23], v[204:205], v[82:83]
	v_pk_fma_f32 v[84:85], v[20:21], v[204:205], v[84:85]
	v_pk_fma_f32 v[86:87], v[18:19], v[204:205], v[86:87]
	v_pk_fma_f32 v[88:89], v[16:17], v[204:205], v[88:89]
	ds_read_b32 v161, v2 offset:17408
	s_waitcnt lgkmcnt(12)
	v_lshlrev_b32_e32 v204, 16, v149
	v_and_b32_e32 v205, 0xffff0000, v149
	v_pk_fma_f32 v[80:81], v[26:27], v[204:205], v[80:81]
	v_pk_fma_f32 v[82:83], v[24:25], v[204:205], v[82:83]
	v_pk_fma_f32 v[84:85], v[22:23], v[204:205], v[84:85]
	v_pk_fma_f32 v[86:87], v[20:21], v[204:205], v[86:87]
	v_pk_fma_f32 v[88:89], v[18:19], v[204:205], v[88:89]
	v_pk_fma_f32 v[90:91], v[16:17], v[204:205], v[90:91]
	ds_read_b32 v162, v2 offset:18432
	s_waitcnt lgkmcnt(12)
	v_lshlrev_b32_e32 v204, 16, v150
	v_and_b32_e32 v205, 0xffff0000, v150
	v_pk_fma_f32 v[80:81], v[28:29], v[204:205], v[80:81]
	v_pk_fma_f32 v[82:83], v[26:27], v[204:205], v[82:83]
	v_pk_fma_f32 v[84:85], v[24:25], v[204:205], v[84:85]
	v_pk_fma_f32 v[86:87], v[22:23], v[204:205], v[86:87]
	v_pk_fma_f32 v[88:89], v[20:21], v[204:205], v[88:89]
	v_pk_fma_f32 v[90:91], v[18:19], v[204:205], v[90:91]
	v_pk_fma_f32 v[92:93], v[16:17], v[204:205], v[92:93]
	ds_read_b32 v163, v2 offset:19456
	s_waitcnt lgkmcnt(12)
	v_lshlrev_b32_e32 v204, 16, v151
	v_and_b32_e32 v205, 0xffff0000, v151
	v_pk_fma_f32 v[80:81], v[30:31], v[204:205], v[80:81]
	v_pk_fma_f32 v[82:83], v[28:29], v[204:205], v[82:83]
	v_pk_fma_f32 v[84:85], v[26:27], v[204:205], v[84:85]
	v_pk_fma_f32 v[86:87], v[24:25], v[204:205], v[86:87]
	v_pk_fma_f32 v[88:89], v[22:23], v[204:205], v[88:89]
	v_pk_fma_f32 v[90:91], v[20:21], v[204:205], v[90:91]
	v_pk_fma_f32 v[92:93], v[18:19], v[204:205], v[92:93]
	v_pk_fma_f32 v[94:95], v[16:17], v[204:205], v[94:95]
	ds_read_b32 v164, v2 offset:20480
	s_waitcnt lgkmcnt(12)
	v_lshlrev_b32_e32 v204, 16, v152
	v_and_b32_e32 v205, 0xffff0000, v152
	v_pk_fma_f32 v[80:81], v[32:33], v[204:205], v[80:81]
	v_pk_fma_f32 v[82:83], v[30:31], v[204:205], v[82:83]
	v_pk_fma_f32 v[84:85], v[28:29], v[204:205], v[84:85]
	v_pk_fma_f32 v[86:87], v[26:27], v[204:205], v[86:87]
	v_pk_fma_f32 v[88:89], v[24:25], v[204:205], v[88:89]
	v_pk_fma_f32 v[90:91], v[22:23], v[204:205], v[90:91]
	v_pk_fma_f32 v[92:93], v[20:21], v[204:205], v[92:93]
	v_pk_fma_f32 v[94:95], v[18:19], v[204:205], v[94:95]
	v_pk_fma_f32 v[96:97], v[16:17], v[204:205], v[96:97]
	ds_read_b32 v165, v2 offset:21504
	s_waitcnt lgkmcnt(12)
	v_lshlrev_b32_e32 v204, 16, v153
	v_and_b32_e32 v205, 0xffff0000, v153
	v_pk_fma_f32 v[80:81], v[34:35], v[204:205], v[80:81]
	v_pk_fma_f32 v[82:83], v[32:33], v[204:205], v[82:83]
	v_pk_fma_f32 v[84:85], v[30:31], v[204:205], v[84:85]
	v_pk_fma_f32 v[86:87], v[28:29], v[204:205], v[86:87]
	v_pk_fma_f32 v[88:89], v[26:27], v[204:205], v[88:89]
	v_pk_fma_f32 v[90:91], v[24:25], v[204:205], v[90:91]
	v_pk_fma_f32 v[92:93], v[22:23], v[204:205], v[92:93]
	v_pk_fma_f32 v[94:95], v[20:21], v[204:205], v[94:95]
	v_pk_fma_f32 v[96:97], v[18:19], v[204:205], v[96:97]
	v_pk_fma_f32 v[98:99], v[16:17], v[204:205], v[98:99]
	ds_read_b32 v166, v2 offset:22528
	s_waitcnt lgkmcnt(12)
	v_lshlrev_b32_e32 v204, 16, v154
	v_and_b32_e32 v205, 0xffff0000, v154
	v_pk_fma_f32 v[80:81], v[36:37], v[204:205], v[80:81]
	v_pk_fma_f32 v[82:83], v[34:35], v[204:205], v[82:83]
	v_pk_fma_f32 v[84:85], v[32:33], v[204:205], v[84:85]
	v_pk_fma_f32 v[86:87], v[30:31], v[204:205], v[86:87]
	v_pk_fma_f32 v[88:89], v[28:29], v[204:205], v[88:89]
	v_pk_fma_f32 v[90:91], v[26:27], v[204:205], v[90:91]
	v_pk_fma_f32 v[92:93], v[24:25], v[204:205], v[92:93]
	v_pk_fma_f32 v[94:95], v[22:23], v[204:205], v[94:95]
	v_pk_fma_f32 v[96:97], v[20:21], v[204:205], v[96:97]
	v_pk_fma_f32 v[98:99], v[18:19], v[204:205], v[98:99]
	v_pk_fma_f32 v[100:101], v[16:17], v[204:205], v[100:101]
	ds_read_b32 v167, v2 offset:23552
	s_waitcnt lgkmcnt(12)
	v_lshlrev_b32_e32 v204, 16, v155
	v_and_b32_e32 v205, 0xffff0000, v155
	v_pk_fma_f32 v[80:81], v[38:39], v[204:205], v[80:81]
	v_pk_fma_f32 v[82:83], v[36:37], v[204:205], v[82:83]
	v_pk_fma_f32 v[84:85], v[34:35], v[204:205], v[84:85]
	v_pk_fma_f32 v[86:87], v[32:33], v[204:205], v[86:87]
	v_pk_fma_f32 v[88:89], v[30:31], v[204:205], v[88:89]
	v_pk_fma_f32 v[90:91], v[28:29], v[204:205], v[90:91]
	v_pk_fma_f32 v[92:93], v[26:27], v[204:205], v[92:93]
	v_pk_fma_f32 v[94:95], v[24:25], v[204:205], v[94:95]
	v_pk_fma_f32 v[96:97], v[22:23], v[204:205], v[96:97]
	v_pk_fma_f32 v[98:99], v[20:21], v[204:205], v[98:99]
	v_pk_fma_f32 v[100:101], v[18:19], v[204:205], v[100:101]
	v_pk_fma_f32 v[102:103], v[16:17], v[204:205], v[102:103]
	ds_read_b32 v168, v2 offset:24576
	s_waitcnt lgkmcnt(12)
	v_lshlrev_b32_e32 v204, 16, v156
	v_and_b32_e32 v205, 0xffff0000, v156
	v_pk_fma_f32 v[80:81], v[40:41], v[204:205], v[80:81]
	v_pk_fma_f32 v[82:83], v[38:39], v[204:205], v[82:83]
	v_pk_fma_f32 v[84:85], v[36:37], v[204:205], v[84:85]
	v_pk_fma_f32 v[86:87], v[34:35], v[204:205], v[86:87]
	v_pk_fma_f32 v[88:89], v[32:33], v[204:205], v[88:89]
	v_pk_fma_f32 v[90:91], v[30:31], v[204:205], v[90:91]
	v_pk_fma_f32 v[92:93], v[28:29], v[204:205], v[92:93]
	v_pk_fma_f32 v[94:95], v[26:27], v[204:205], v[94:95]
	v_pk_fma_f32 v[96:97], v[24:25], v[204:205], v[96:97]
	v_pk_fma_f32 v[98:99], v[22:23], v[204:205], v[98:99]
	v_pk_fma_f32 v[100:101], v[20:21], v[204:205], v[100:101]
	v_pk_fma_f32 v[102:103], v[18:19], v[204:205], v[102:103]
	v_pk_fma_f32 v[104:105], v[16:17], v[204:205], v[104:105]
	ds_read_b32 v169, v2 offset:25600
	s_waitcnt lgkmcnt(12)
	v_lshlrev_b32_e32 v204, 16, v157
	v_and_b32_e32 v205, 0xffff0000, v157
	v_pk_fma_f32 v[80:81], v[42:43], v[204:205], v[80:81]
	v_pk_fma_f32 v[82:83], v[40:41], v[204:205], v[82:83]
	v_pk_fma_f32 v[84:85], v[38:39], v[204:205], v[84:85]
	v_pk_fma_f32 v[86:87], v[36:37], v[204:205], v[86:87]
	v_pk_fma_f32 v[88:89], v[34:35], v[204:205], v[88:89]
	v_pk_fma_f32 v[90:91], v[32:33], v[204:205], v[90:91]
	v_pk_fma_f32 v[92:93], v[30:31], v[204:205], v[92:93]
	v_pk_fma_f32 v[94:95], v[28:29], v[204:205], v[94:95]
	v_pk_fma_f32 v[96:97], v[26:27], v[204:205], v[96:97]
	v_pk_fma_f32 v[98:99], v[24:25], v[204:205], v[98:99]
	v_pk_fma_f32 v[100:101], v[22:23], v[204:205], v[100:101]
	v_pk_fma_f32 v[102:103], v[20:21], v[204:205], v[102:103]
	v_pk_fma_f32 v[104:105], v[18:19], v[204:205], v[104:105]
	v_pk_fma_f32 v[106:107], v[16:17], v[204:205], v[106:107]
	ds_read_b32 v170, v2 offset:26624
	s_waitcnt lgkmcnt(12)
	v_lshlrev_b32_e32 v204, 16, v158
	v_and_b32_e32 v205, 0xffff0000, v158
	v_pk_fma_f32 v[80:81], v[44:45], v[204:205], v[80:81]
	v_pk_fma_f32 v[82:83], v[42:43], v[204:205], v[82:83]
	v_pk_fma_f32 v[84:85], v[40:41], v[204:205], v[84:85]
	v_pk_fma_f32 v[86:87], v[38:39], v[204:205], v[86:87]
	v_pk_fma_f32 v[88:89], v[36:37], v[204:205], v[88:89]
	v_pk_fma_f32 v[90:91], v[34:35], v[204:205], v[90:91]
	v_pk_fma_f32 v[92:93], v[32:33], v[204:205], v[92:93]
	v_pk_fma_f32 v[94:95], v[30:31], v[204:205], v[94:95]
	v_pk_fma_f32 v[96:97], v[28:29], v[204:205], v[96:97]
	v_pk_fma_f32 v[98:99], v[26:27], v[204:205], v[98:99]
	v_pk_fma_f32 v[100:101], v[24:25], v[204:205], v[100:101]
	v_pk_fma_f32 v[102:103], v[22:23], v[204:205], v[102:103]
	v_pk_fma_f32 v[104:105], v[20:21], v[204:205], v[104:105]
	v_pk_fma_f32 v[106:107], v[18:19], v[204:205], v[106:107]
	v_pk_fma_f32 v[108:109], v[16:17], v[204:205], v[108:109]
	ds_read_b32 v171, v2 offset:27648
	s_waitcnt lgkmcnt(12)
	v_lshlrev_b32_e32 v204, 16, v159
	v_and_b32_e32 v205, 0xffff0000, v159
	v_pk_fma_f32 v[80:81], v[46:47], v[204:205], v[80:81]
	v_pk_fma_f32 v[82:83], v[44:45], v[204:205], v[82:83]
	v_pk_fma_f32 v[84:85], v[42:43], v[204:205], v[84:85]
	v_pk_fma_f32 v[86:87], v[40:41], v[204:205], v[86:87]
	v_pk_fma_f32 v[88:89], v[38:39], v[204:205], v[88:89]
	v_pk_fma_f32 v[90:91], v[36:37], v[204:205], v[90:91]
	v_pk_fma_f32 v[92:93], v[34:35], v[204:205], v[92:93]
	v_pk_fma_f32 v[94:95], v[32:33], v[204:205], v[94:95]
	v_pk_fma_f32 v[96:97], v[30:31], v[204:205], v[96:97]
	v_pk_fma_f32 v[98:99], v[28:29], v[204:205], v[98:99]
	v_pk_fma_f32 v[100:101], v[26:27], v[204:205], v[100:101]
	v_pk_fma_f32 v[102:103], v[24:25], v[204:205], v[102:103]
	v_pk_fma_f32 v[104:105], v[22:23], v[204:205], v[104:105]
	v_pk_fma_f32 v[106:107], v[20:21], v[204:205], v[106:107]
	v_pk_fma_f32 v[108:109], v[18:19], v[204:205], v[108:109]
	v_pk_fma_f32 v[110:111], v[16:17], v[204:205], v[110:111]
	ds_read_b32 v172, v2 offset:28672
	s_waitcnt lgkmcnt(12)
	v_lshlrev_b32_e32 v204, 16, v160
	v_and_b32_e32 v205, 0xffff0000, v160
	v_pk_fma_f32 v[80:81], v[48:49], v[204:205], v[80:81]
	v_pk_fma_f32 v[82:83], v[46:47], v[204:205], v[82:83]
	v_pk_fma_f32 v[84:85], v[44:45], v[204:205], v[84:85]
	v_pk_fma_f32 v[86:87], v[42:43], v[204:205], v[86:87]
	v_pk_fma_f32 v[88:89], v[40:41], v[204:205], v[88:89]
	v_pk_fma_f32 v[90:91], v[38:39], v[204:205], v[90:91]
	v_pk_fma_f32 v[92:93], v[36:37], v[204:205], v[92:93]
	v_pk_fma_f32 v[94:95], v[34:35], v[204:205], v[94:95]
	v_pk_fma_f32 v[96:97], v[32:33], v[204:205], v[96:97]
	v_pk_fma_f32 v[98:99], v[30:31], v[204:205], v[98:99]
	v_pk_fma_f32 v[100:101], v[28:29], v[204:205], v[100:101]
	v_pk_fma_f32 v[102:103], v[26:27], v[204:205], v[102:103]
	v_pk_fma_f32 v[104:105], v[24:25], v[204:205], v[104:105]
	v_pk_fma_f32 v[106:107], v[22:23], v[204:205], v[106:107]
	v_pk_fma_f32 v[108:109], v[20:21], v[204:205], v[108:109]
	v_pk_fma_f32 v[110:111], v[18:19], v[204:205], v[110:111]
	ds_read_b32 v173, v2 offset:29696
	s_waitcnt lgkmcnt(12)
	v_lshlrev_b32_e32 v204, 16, v161
	v_and_b32_e32 v205, 0xffff0000, v161
	v_pk_fma_f32 v[80:81], v[50:51], v[204:205], v[80:81]
	v_pk_fma_f32 v[82:83], v[48:49], v[204:205], v[82:83]
	v_pk_fma_f32 v[84:85], v[46:47], v[204:205], v[84:85]
	v_pk_fma_f32 v[86:87], v[44:45], v[204:205], v[86:87]
	v_pk_fma_f32 v[88:89], v[42:43], v[204:205], v[88:89]
	v_pk_fma_f32 v[90:91], v[40:41], v[204:205], v[90:91]
	v_pk_fma_f32 v[92:93], v[38:39], v[204:205], v[92:93]
	v_pk_fma_f32 v[94:95], v[36:37], v[204:205], v[94:95]
	v_pk_fma_f32 v[96:97], v[34:35], v[204:205], v[96:97]
	v_pk_fma_f32 v[98:99], v[32:33], v[204:205], v[98:99]
	v_pk_fma_f32 v[100:101], v[30:31], v[204:205], v[100:101]
	v_pk_fma_f32 v[102:103], v[28:29], v[204:205], v[102:103]
	v_pk_fma_f32 v[104:105], v[26:27], v[204:205], v[104:105]
	v_pk_fma_f32 v[106:107], v[24:25], v[204:205], v[106:107]
	v_pk_fma_f32 v[108:109], v[22:23], v[204:205], v[108:109]
	v_pk_fma_f32 v[110:111], v[20:21], v[204:205], v[110:111]
	ds_read_b32 v174, v2 offset:30720
	s_waitcnt lgkmcnt(12)
	v_lshlrev_b32_e32 v204, 16, v162
	v_and_b32_e32 v205, 0xffff0000, v162
	v_pk_fma_f32 v[80:81], v[52:53], v[204:205], v[80:81]
	v_pk_fma_f32 v[82:83], v[50:51], v[204:205], v[82:83]
	v_pk_fma_f32 v[84:85], v[48:49], v[204:205], v[84:85]
	v_pk_fma_f32 v[86:87], v[46:47], v[204:205], v[86:87]
	v_pk_fma_f32 v[88:89], v[44:45], v[204:205], v[88:89]
	v_pk_fma_f32 v[90:91], v[42:43], v[204:205], v[90:91]
	v_pk_fma_f32 v[92:93], v[40:41], v[204:205], v[92:93]
	v_pk_fma_f32 v[94:95], v[38:39], v[204:205], v[94:95]
	v_pk_fma_f32 v[96:97], v[36:37], v[204:205], v[96:97]
	v_pk_fma_f32 v[98:99], v[34:35], v[204:205], v[98:99]
	v_pk_fma_f32 v[100:101], v[32:33], v[204:205], v[100:101]
	v_pk_fma_f32 v[102:103], v[30:31], v[204:205], v[102:103]
	v_pk_fma_f32 v[104:105], v[28:29], v[204:205], v[104:105]
	v_pk_fma_f32 v[106:107], v[26:27], v[204:205], v[106:107]
	v_pk_fma_f32 v[108:109], v[24:25], v[204:205], v[108:109]
	v_pk_fma_f32 v[110:111], v[22:23], v[204:205], v[110:111]
	ds_read_b32 v175, v2 offset:31744
	s_waitcnt lgkmcnt(12)
	v_lshlrev_b32_e32 v204, 16, v163
	v_and_b32_e32 v205, 0xffff0000, v163
	v_pk_fma_f32 v[80:81], v[54:55], v[204:205], v[80:81]
	v_pk_fma_f32 v[82:83], v[52:53], v[204:205], v[82:83]
	v_pk_fma_f32 v[84:85], v[50:51], v[204:205], v[84:85]
	v_pk_fma_f32 v[86:87], v[48:49], v[204:205], v[86:87]
	v_pk_fma_f32 v[88:89], v[46:47], v[204:205], v[88:89]
	v_pk_fma_f32 v[90:91], v[44:45], v[204:205], v[90:91]
	v_pk_fma_f32 v[92:93], v[42:43], v[204:205], v[92:93]
	v_pk_fma_f32 v[94:95], v[40:41], v[204:205], v[94:95]
	v_pk_fma_f32 v[96:97], v[38:39], v[204:205], v[96:97]
	v_pk_fma_f32 v[98:99], v[36:37], v[204:205], v[98:99]
	v_pk_fma_f32 v[100:101], v[34:35], v[204:205], v[100:101]
	v_pk_fma_f32 v[102:103], v[32:33], v[204:205], v[102:103]
	v_pk_fma_f32 v[104:105], v[30:31], v[204:205], v[104:105]
	v_pk_fma_f32 v[106:107], v[28:29], v[204:205], v[106:107]
	v_pk_fma_f32 v[108:109], v[26:27], v[204:205], v[108:109]
	v_pk_fma_f32 v[110:111], v[24:25], v[204:205], v[110:111]
	ds_read_b32 v176, v2 offset:32768
	s_waitcnt lgkmcnt(12)
	v_lshlrev_b32_e32 v204, 16, v164
	v_and_b32_e32 v205, 0xffff0000, v164
	v_pk_fma_f32 v[80:81], v[56:57], v[204:205], v[80:81]
	v_pk_fma_f32 v[82:83], v[54:55], v[204:205], v[82:83]
	v_pk_fma_f32 v[84:85], v[52:53], v[204:205], v[84:85]
	v_pk_fma_f32 v[86:87], v[50:51], v[204:205], v[86:87]
	v_pk_fma_f32 v[88:89], v[48:49], v[204:205], v[88:89]
	v_pk_fma_f32 v[90:91], v[46:47], v[204:205], v[90:91]
	v_pk_fma_f32 v[92:93], v[44:45], v[204:205], v[92:93]
	v_pk_fma_f32 v[94:95], v[42:43], v[204:205], v[94:95]
	v_pk_fma_f32 v[96:97], v[40:41], v[204:205], v[96:97]
	v_pk_fma_f32 v[98:99], v[38:39], v[204:205], v[98:99]
	v_pk_fma_f32 v[100:101], v[36:37], v[204:205], v[100:101]
	v_pk_fma_f32 v[102:103], v[34:35], v[204:205], v[102:103]
	v_pk_fma_f32 v[104:105], v[32:33], v[204:205], v[104:105]
	v_pk_fma_f32 v[106:107], v[30:31], v[204:205], v[106:107]
	v_pk_fma_f32 v[108:109], v[28:29], v[204:205], v[108:109]
	v_pk_fma_f32 v[110:111], v[26:27], v[204:205], v[110:111]
	ds_read_b32 v177, v2 offset:33792
	s_waitcnt lgkmcnt(12)
	v_lshlrev_b32_e32 v204, 16, v165
	v_and_b32_e32 v205, 0xffff0000, v165
	v_pk_fma_f32 v[80:81], v[58:59], v[204:205], v[80:81]
	v_pk_fma_f32 v[82:83], v[56:57], v[204:205], v[82:83]
	v_pk_fma_f32 v[84:85], v[54:55], v[204:205], v[84:85]
	v_pk_fma_f32 v[86:87], v[52:53], v[204:205], v[86:87]
	v_pk_fma_f32 v[88:89], v[50:51], v[204:205], v[88:89]
	v_pk_fma_f32 v[90:91], v[48:49], v[204:205], v[90:91]
	v_pk_fma_f32 v[92:93], v[46:47], v[204:205], v[92:93]
	v_pk_fma_f32 v[94:95], v[44:45], v[204:205], v[94:95]
	v_pk_fma_f32 v[96:97], v[42:43], v[204:205], v[96:97]
	v_pk_fma_f32 v[98:99], v[40:41], v[204:205], v[98:99]
	v_pk_fma_f32 v[100:101], v[38:39], v[204:205], v[100:101]
	v_pk_fma_f32 v[102:103], v[36:37], v[204:205], v[102:103]
	v_pk_fma_f32 v[104:105], v[34:35], v[204:205], v[104:105]
	v_pk_fma_f32 v[106:107], v[32:33], v[204:205], v[106:107]
	v_pk_fma_f32 v[108:109], v[30:31], v[204:205], v[108:109]
	v_pk_fma_f32 v[110:111], v[28:29], v[204:205], v[110:111]
	ds_read_b32 v178, v2 offset:34816
	s_waitcnt lgkmcnt(12)
	v_lshlrev_b32_e32 v204, 16, v166
	v_and_b32_e32 v205, 0xffff0000, v166
	v_pk_fma_f32 v[80:81], v[60:61], v[204:205], v[80:81]
	v_pk_fma_f32 v[82:83], v[58:59], v[204:205], v[82:83]
	v_pk_fma_f32 v[84:85], v[56:57], v[204:205], v[84:85]
	v_pk_fma_f32 v[86:87], v[54:55], v[204:205], v[86:87]
	v_pk_fma_f32 v[88:89], v[52:53], v[204:205], v[88:89]
	v_pk_fma_f32 v[90:91], v[50:51], v[204:205], v[90:91]
	v_pk_fma_f32 v[92:93], v[48:49], v[204:205], v[92:93]
	v_pk_fma_f32 v[94:95], v[46:47], v[204:205], v[94:95]
	v_pk_fma_f32 v[96:97], v[44:45], v[204:205], v[96:97]
	v_pk_fma_f32 v[98:99], v[42:43], v[204:205], v[98:99]
	v_pk_fma_f32 v[100:101], v[40:41], v[204:205], v[100:101]
	v_pk_fma_f32 v[102:103], v[38:39], v[204:205], v[102:103]
	v_pk_fma_f32 v[104:105], v[36:37], v[204:205], v[104:105]
	v_pk_fma_f32 v[106:107], v[34:35], v[204:205], v[106:107]
	v_pk_fma_f32 v[108:109], v[32:33], v[204:205], v[108:109]
	v_pk_fma_f32 v[110:111], v[30:31], v[204:205], v[110:111]
	ds_read_b32 v179, v2 offset:35840
	s_waitcnt lgkmcnt(12)
	v_lshlrev_b32_e32 v204, 16, v167
	v_and_b32_e32 v205, 0xffff0000, v167
	v_pk_fma_f32 v[80:81], v[62:63], v[204:205], v[80:81]
	v_pk_fma_f32 v[82:83], v[60:61], v[204:205], v[82:83]
	v_pk_fma_f32 v[84:85], v[58:59], v[204:205], v[84:85]
	v_pk_fma_f32 v[86:87], v[56:57], v[204:205], v[86:87]
	v_pk_fma_f32 v[88:89], v[54:55], v[204:205], v[88:89]
	v_pk_fma_f32 v[90:91], v[52:53], v[204:205], v[90:91]
	v_pk_fma_f32 v[92:93], v[50:51], v[204:205], v[92:93]
	v_pk_fma_f32 v[94:95], v[48:49], v[204:205], v[94:95]
	v_pk_fma_f32 v[96:97], v[46:47], v[204:205], v[96:97]
	v_pk_fma_f32 v[98:99], v[44:45], v[204:205], v[98:99]
	v_pk_fma_f32 v[100:101], v[42:43], v[204:205], v[100:101]
	v_pk_fma_f32 v[102:103], v[40:41], v[204:205], v[102:103]
	v_pk_fma_f32 v[104:105], v[38:39], v[204:205], v[104:105]
	v_pk_fma_f32 v[106:107], v[36:37], v[204:205], v[106:107]
	v_pk_fma_f32 v[108:109], v[34:35], v[204:205], v[108:109]
	v_pk_fma_f32 v[110:111], v[32:33], v[204:205], v[110:111]
	ds_read_b32 v180, v2 offset:36864
	s_waitcnt lgkmcnt(12)
	v_lshlrev_b32_e32 v204, 16, v168
	v_and_b32_e32 v205, 0xffff0000, v168
	v_pk_fma_f32 v[80:81], v[64:65], v[204:205], v[80:81]
	v_pk_fma_f32 v[82:83], v[62:63], v[204:205], v[82:83]
	v_pk_fma_f32 v[84:85], v[60:61], v[204:205], v[84:85]
	v_pk_fma_f32 v[86:87], v[58:59], v[204:205], v[86:87]
	v_pk_fma_f32 v[88:89], v[56:57], v[204:205], v[88:89]
	v_pk_fma_f32 v[90:91], v[54:55], v[204:205], v[90:91]
	v_pk_fma_f32 v[92:93], v[52:53], v[204:205], v[92:93]
	v_pk_fma_f32 v[94:95], v[50:51], v[204:205], v[94:95]
	v_pk_fma_f32 v[96:97], v[48:49], v[204:205], v[96:97]
	v_pk_fma_f32 v[98:99], v[46:47], v[204:205], v[98:99]
	v_pk_fma_f32 v[100:101], v[44:45], v[204:205], v[100:101]
	v_pk_fma_f32 v[102:103], v[42:43], v[204:205], v[102:103]
	v_pk_fma_f32 v[104:105], v[40:41], v[204:205], v[104:105]
	v_pk_fma_f32 v[106:107], v[38:39], v[204:205], v[106:107]
	v_pk_fma_f32 v[108:109], v[36:37], v[204:205], v[108:109]
	v_pk_fma_f32 v[110:111], v[34:35], v[204:205], v[110:111]
	ds_read_b32 v184, v2 offset:37888
	s_waitcnt lgkmcnt(12)
	v_lshlrev_b32_e32 v204, 16, v169
	v_and_b32_e32 v205, 0xffff0000, v169
	v_pk_fma_f32 v[80:81], v[66:67], v[204:205], v[80:81]
	v_pk_fma_f32 v[82:83], v[64:65], v[204:205], v[82:83]
	v_pk_fma_f32 v[84:85], v[62:63], v[204:205], v[84:85]
	v_pk_fma_f32 v[86:87], v[60:61], v[204:205], v[86:87]
	v_pk_fma_f32 v[88:89], v[58:59], v[204:205], v[88:89]
	v_pk_fma_f32 v[90:91], v[56:57], v[204:205], v[90:91]
	v_pk_fma_f32 v[92:93], v[54:55], v[204:205], v[92:93]
	v_pk_fma_f32 v[94:95], v[52:53], v[204:205], v[94:95]
	v_pk_fma_f32 v[96:97], v[50:51], v[204:205], v[96:97]
	v_pk_fma_f32 v[98:99], v[48:49], v[204:205], v[98:99]
	v_pk_fma_f32 v[100:101], v[46:47], v[204:205], v[100:101]
	v_pk_fma_f32 v[102:103], v[44:45], v[204:205], v[102:103]
	v_pk_fma_f32 v[104:105], v[42:43], v[204:205], v[104:105]
	v_pk_fma_f32 v[106:107], v[40:41], v[204:205], v[106:107]
	v_pk_fma_f32 v[108:109], v[38:39], v[204:205], v[108:109]
	v_pk_fma_f32 v[110:111], v[36:37], v[204:205], v[110:111]
	ds_read_b32 v185, v2 offset:38912
	s_waitcnt lgkmcnt(12)
	v_lshlrev_b32_e32 v204, 16, v170
	v_and_b32_e32 v205, 0xffff0000, v170
	v_pk_fma_f32 v[80:81], v[68:69], v[204:205], v[80:81]
	v_pk_fma_f32 v[82:83], v[66:67], v[204:205], v[82:83]
	v_pk_fma_f32 v[84:85], v[64:65], v[204:205], v[84:85]
	v_pk_fma_f32 v[86:87], v[62:63], v[204:205], v[86:87]
	v_pk_fma_f32 v[88:89], v[60:61], v[204:205], v[88:89]
	v_pk_fma_f32 v[90:91], v[58:59], v[204:205], v[90:91]
	v_pk_fma_f32 v[92:93], v[56:57], v[204:205], v[92:93]
	v_pk_fma_f32 v[94:95], v[54:55], v[204:205], v[94:95]
	v_pk_fma_f32 v[96:97], v[52:53], v[204:205], v[96:97]
	v_pk_fma_f32 v[98:99], v[50:51], v[204:205], v[98:99]
	v_pk_fma_f32 v[100:101], v[48:49], v[204:205], v[100:101]
	v_pk_fma_f32 v[102:103], v[46:47], v[204:205], v[102:103]
	v_pk_fma_f32 v[104:105], v[44:45], v[204:205], v[104:105]
	v_pk_fma_f32 v[106:107], v[42:43], v[204:205], v[106:107]
	v_pk_fma_f32 v[108:109], v[40:41], v[204:205], v[108:109]
	v_pk_fma_f32 v[110:111], v[38:39], v[204:205], v[110:111]
	ds_read_b32 v186, v2 offset:39936
	s_waitcnt lgkmcnt(12)
	v_lshlrev_b32_e32 v204, 16, v171
	v_and_b32_e32 v205, 0xffff0000, v171
	v_pk_fma_f32 v[80:81], v[70:71], v[204:205], v[80:81]
	v_pk_fma_f32 v[82:83], v[68:69], v[204:205], v[82:83]
	v_pk_fma_f32 v[84:85], v[66:67], v[204:205], v[84:85]
	v_pk_fma_f32 v[86:87], v[64:65], v[204:205], v[86:87]
	v_pk_fma_f32 v[88:89], v[62:63], v[204:205], v[88:89]
	v_pk_fma_f32 v[90:91], v[60:61], v[204:205], v[90:91]
	v_pk_fma_f32 v[92:93], v[58:59], v[204:205], v[92:93]
	v_pk_fma_f32 v[94:95], v[56:57], v[204:205], v[94:95]
	v_pk_fma_f32 v[96:97], v[54:55], v[204:205], v[96:97]
	v_pk_fma_f32 v[98:99], v[52:53], v[204:205], v[98:99]
	v_pk_fma_f32 v[100:101], v[50:51], v[204:205], v[100:101]
	v_pk_fma_f32 v[102:103], v[48:49], v[204:205], v[102:103]
	v_pk_fma_f32 v[104:105], v[46:47], v[204:205], v[104:105]
	v_pk_fma_f32 v[106:107], v[44:45], v[204:205], v[106:107]
	v_pk_fma_f32 v[108:109], v[42:43], v[204:205], v[108:109]
	v_pk_fma_f32 v[110:111], v[40:41], v[204:205], v[110:111]
	ds_read_b32 v187, v2 offset:40960
	s_waitcnt lgkmcnt(12)
	v_lshlrev_b32_e32 v204, 16, v172
	v_and_b32_e32 v205, 0xffff0000, v172
	v_pk_fma_f32 v[80:81], v[72:73], v[204:205], v[80:81]
	v_pk_fma_f32 v[82:83], v[70:71], v[204:205], v[82:83]
	v_pk_fma_f32 v[84:85], v[68:69], v[204:205], v[84:85]
	v_pk_fma_f32 v[86:87], v[66:67], v[204:205], v[86:87]
	v_pk_fma_f32 v[88:89], v[64:65], v[204:205], v[88:89]
	v_pk_fma_f32 v[90:91], v[62:63], v[204:205], v[90:91]
	v_pk_fma_f32 v[92:93], v[60:61], v[204:205], v[92:93]
	v_pk_fma_f32 v[94:95], v[58:59], v[204:205], v[94:95]
	v_pk_fma_f32 v[96:97], v[56:57], v[204:205], v[96:97]
	v_pk_fma_f32 v[98:99], v[54:55], v[204:205], v[98:99]
	v_pk_fma_f32 v[100:101], v[52:53], v[204:205], v[100:101]
	v_pk_fma_f32 v[102:103], v[50:51], v[204:205], v[102:103]
	v_pk_fma_f32 v[104:105], v[48:49], v[204:205], v[104:105]
	v_pk_fma_f32 v[106:107], v[46:47], v[204:205], v[106:107]
	v_pk_fma_f32 v[108:109], v[44:45], v[204:205], v[108:109]
	v_pk_fma_f32 v[110:111], v[42:43], v[204:205], v[110:111]
	ds_read_b32 v188, v2 offset:41984
	s_waitcnt lgkmcnt(12)
	v_lshlrev_b32_e32 v204, 16, v173
	v_and_b32_e32 v205, 0xffff0000, v173
	v_pk_fma_f32 v[80:81], v[74:75], v[204:205], v[80:81]
	v_pk_fma_f32 v[82:83], v[72:73], v[204:205], v[82:83]
	v_pk_fma_f32 v[84:85], v[70:71], v[204:205], v[84:85]
	v_pk_fma_f32 v[86:87], v[68:69], v[204:205], v[86:87]
	v_pk_fma_f32 v[88:89], v[66:67], v[204:205], v[88:89]
	v_pk_fma_f32 v[90:91], v[64:65], v[204:205], v[90:91]
	v_pk_fma_f32 v[92:93], v[62:63], v[204:205], v[92:93]
	v_pk_fma_f32 v[94:95], v[60:61], v[204:205], v[94:95]
	v_pk_fma_f32 v[96:97], v[58:59], v[204:205], v[96:97]
	v_pk_fma_f32 v[98:99], v[56:57], v[204:205], v[98:99]
	v_pk_fma_f32 v[100:101], v[54:55], v[204:205], v[100:101]
	v_pk_fma_f32 v[102:103], v[52:53], v[204:205], v[102:103]
	v_pk_fma_f32 v[104:105], v[50:51], v[204:205], v[104:105]
	v_pk_fma_f32 v[106:107], v[48:49], v[204:205], v[106:107]
	v_pk_fma_f32 v[108:109], v[46:47], v[204:205], v[108:109]
	v_pk_fma_f32 v[110:111], v[44:45], v[204:205], v[110:111]
	ds_read_b32 v189, v2 offset:43008
	s_waitcnt lgkmcnt(12)
	v_lshlrev_b32_e32 v204, 16, v174
	v_and_b32_e32 v205, 0xffff0000, v174
	v_pk_fma_f32 v[80:81], v[76:77], v[204:205], v[80:81]
	v_pk_fma_f32 v[82:83], v[74:75], v[204:205], v[82:83]
	v_pk_fma_f32 v[84:85], v[72:73], v[204:205], v[84:85]
	v_pk_fma_f32 v[86:87], v[70:71], v[204:205], v[86:87]
	v_pk_fma_f32 v[88:89], v[68:69], v[204:205], v[88:89]
	v_pk_fma_f32 v[90:91], v[66:67], v[204:205], v[90:91]
	v_pk_fma_f32 v[92:93], v[64:65], v[204:205], v[92:93]
	v_pk_fma_f32 v[94:95], v[62:63], v[204:205], v[94:95]
	v_pk_fma_f32 v[96:97], v[60:61], v[204:205], v[96:97]
	v_pk_fma_f32 v[98:99], v[58:59], v[204:205], v[98:99]
	v_pk_fma_f32 v[100:101], v[56:57], v[204:205], v[100:101]
	v_pk_fma_f32 v[102:103], v[54:55], v[204:205], v[102:103]
	v_pk_fma_f32 v[104:105], v[52:53], v[204:205], v[104:105]
	v_pk_fma_f32 v[106:107], v[50:51], v[204:205], v[106:107]
	v_pk_fma_f32 v[108:109], v[48:49], v[204:205], v[108:109]
	v_pk_fma_f32 v[110:111], v[46:47], v[204:205], v[110:111]
	ds_read_b32 v190, v2 offset:44032
	s_waitcnt lgkmcnt(12)
	v_lshlrev_b32_e32 v204, 16, v175
	v_and_b32_e32 v205, 0xffff0000, v175
	v_pk_fma_f32 v[82:83], v[76:77], v[204:205], v[82:83]
	v_pk_fma_f32 v[84:85], v[74:75], v[204:205], v[84:85]
	v_pk_fma_f32 v[86:87], v[72:73], v[204:205], v[86:87]
	v_pk_fma_f32 v[88:89], v[70:71], v[204:205], v[88:89]
	v_pk_fma_f32 v[90:91], v[68:69], v[204:205], v[90:91]
	v_pk_fma_f32 v[92:93], v[66:67], v[204:205], v[92:93]
	v_pk_fma_f32 v[94:95], v[64:65], v[204:205], v[94:95]
	v_pk_fma_f32 v[96:97], v[62:63], v[204:205], v[96:97]
	v_pk_fma_f32 v[98:99], v[60:61], v[204:205], v[98:99]
	v_pk_fma_f32 v[100:101], v[58:59], v[204:205], v[100:101]
	v_pk_fma_f32 v[102:103], v[56:57], v[204:205], v[102:103]
	v_pk_fma_f32 v[104:105], v[54:55], v[204:205], v[104:105]
	v_pk_fma_f32 v[106:107], v[52:53], v[204:205], v[106:107]
	v_pk_fma_f32 v[108:109], v[50:51], v[204:205], v[108:109]
	v_pk_fma_f32 v[110:111], v[48:49], v[204:205], v[110:111]
	ds_read_b32 v191, v2 offset:45056
	s_waitcnt lgkmcnt(12)
	v_lshlrev_b32_e32 v204, 16, v176
	v_and_b32_e32 v205, 0xffff0000, v176
	v_pk_fma_f32 v[84:85], v[76:77], v[204:205], v[84:85]
	v_pk_fma_f32 v[86:87], v[74:75], v[204:205], v[86:87]
	v_pk_fma_f32 v[88:89], v[72:73], v[204:205], v[88:89]
	v_pk_fma_f32 v[90:91], v[70:71], v[204:205], v[90:91]
	v_pk_fma_f32 v[92:93], v[68:69], v[204:205], v[92:93]
	v_pk_fma_f32 v[94:95], v[66:67], v[204:205], v[94:95]
	v_pk_fma_f32 v[96:97], v[64:65], v[204:205], v[96:97]
	v_pk_fma_f32 v[98:99], v[62:63], v[204:205], v[98:99]
	v_pk_fma_f32 v[100:101], v[60:61], v[204:205], v[100:101]
	v_pk_fma_f32 v[102:103], v[58:59], v[204:205], v[102:103]
	v_pk_fma_f32 v[104:105], v[56:57], v[204:205], v[104:105]
	v_pk_fma_f32 v[106:107], v[54:55], v[204:205], v[106:107]
	v_pk_fma_f32 v[108:109], v[52:53], v[204:205], v[108:109]
	v_pk_fma_f32 v[110:111], v[50:51], v[204:205], v[110:111]
	ds_read_b32 v192, v2 offset:46080
	s_waitcnt lgkmcnt(12)
	v_lshlrev_b32_e32 v204, 16, v177
	v_and_b32_e32 v205, 0xffff0000, v177
	v_pk_fma_f32 v[86:87], v[76:77], v[204:205], v[86:87]
	v_pk_fma_f32 v[88:89], v[74:75], v[204:205], v[88:89]
	v_pk_fma_f32 v[90:91], v[72:73], v[204:205], v[90:91]
	v_pk_fma_f32 v[92:93], v[70:71], v[204:205], v[92:93]
	v_pk_fma_f32 v[94:95], v[68:69], v[204:205], v[94:95]
	v_pk_fma_f32 v[96:97], v[66:67], v[204:205], v[96:97]
	v_pk_fma_f32 v[98:99], v[64:65], v[204:205], v[98:99]
	v_pk_fma_f32 v[100:101], v[62:63], v[204:205], v[100:101]
	v_pk_fma_f32 v[102:103], v[60:61], v[204:205], v[102:103]
	v_pk_fma_f32 v[104:105], v[58:59], v[204:205], v[104:105]
	v_pk_fma_f32 v[106:107], v[56:57], v[204:205], v[106:107]
	v_pk_fma_f32 v[108:109], v[54:55], v[204:205], v[108:109]
	v_pk_fma_f32 v[110:111], v[52:53], v[204:205], v[110:111]
	s_waitcnt lgkmcnt(11)
	v_lshlrev_b32_e32 v204, 16, v178
	v_and_b32_e32 v205, 0xffff0000, v178
	v_pk_fma_f32 v[88:89], v[76:77], v[204:205], v[88:89]
	v_pk_fma_f32 v[90:91], v[74:75], v[204:205], v[90:91]
	v_pk_fma_f32 v[92:93], v[72:73], v[204:205], v[92:93]
	v_pk_fma_f32 v[94:95], v[70:71], v[204:205], v[94:95]
	v_pk_fma_f32 v[96:97], v[68:69], v[204:205], v[96:97]
	v_pk_fma_f32 v[98:99], v[66:67], v[204:205], v[98:99]
	v_pk_fma_f32 v[100:101], v[64:65], v[204:205], v[100:101]
	v_pk_fma_f32 v[102:103], v[62:63], v[204:205], v[102:103]
	v_pk_fma_f32 v[104:105], v[60:61], v[204:205], v[104:105]
	v_pk_fma_f32 v[106:107], v[58:59], v[204:205], v[106:107]
	v_pk_fma_f32 v[108:109], v[56:57], v[204:205], v[108:109]
	v_pk_fma_f32 v[110:111], v[54:55], v[204:205], v[110:111]
	s_waitcnt lgkmcnt(10)
	v_lshlrev_b32_e32 v204, 16, v179
	v_and_b32_e32 v205, 0xffff0000, v179
	v_pk_fma_f32 v[90:91], v[76:77], v[204:205], v[90:91]
	v_pk_fma_f32 v[92:93], v[74:75], v[204:205], v[92:93]
	v_pk_fma_f32 v[94:95], v[72:73], v[204:205], v[94:95]
	v_pk_fma_f32 v[96:97], v[70:71], v[204:205], v[96:97]
	v_pk_fma_f32 v[98:99], v[68:69], v[204:205], v[98:99]
	v_pk_fma_f32 v[100:101], v[66:67], v[204:205], v[100:101]
	v_pk_fma_f32 v[102:103], v[64:65], v[204:205], v[102:103]
	v_pk_fma_f32 v[104:105], v[62:63], v[204:205], v[104:105]
	v_pk_fma_f32 v[106:107], v[60:61], v[204:205], v[106:107]
	v_pk_fma_f32 v[108:109], v[58:59], v[204:205], v[108:109]
	v_pk_fma_f32 v[110:111], v[56:57], v[204:205], v[110:111]
	s_waitcnt lgkmcnt(9)
	v_lshlrev_b32_e32 v204, 16, v180
	v_and_b32_e32 v205, 0xffff0000, v180
	v_pk_fma_f32 v[92:93], v[76:77], v[204:205], v[92:93]
	v_pk_fma_f32 v[94:95], v[74:75], v[204:205], v[94:95]
	v_pk_fma_f32 v[96:97], v[72:73], v[204:205], v[96:97]
	v_pk_fma_f32 v[98:99], v[70:71], v[204:205], v[98:99]
	v_pk_fma_f32 v[100:101], v[68:69], v[204:205], v[100:101]
	v_pk_fma_f32 v[102:103], v[66:67], v[204:205], v[102:103]
	v_pk_fma_f32 v[104:105], v[64:65], v[204:205], v[104:105]
	v_pk_fma_f32 v[106:107], v[62:63], v[204:205], v[106:107]
	v_pk_fma_f32 v[108:109], v[60:61], v[204:205], v[108:109]
	v_pk_fma_f32 v[110:111], v[58:59], v[204:205], v[110:111]
	s_waitcnt lgkmcnt(8)
	v_lshlrev_b32_e32 v204, 16, v184
	v_and_b32_e32 v205, 0xffff0000, v184
	v_pk_fma_f32 v[94:95], v[76:77], v[204:205], v[94:95]
	v_pk_fma_f32 v[96:97], v[74:75], v[204:205], v[96:97]
	v_pk_fma_f32 v[98:99], v[72:73], v[204:205], v[98:99]
	v_pk_fma_f32 v[100:101], v[70:71], v[204:205], v[100:101]
	v_pk_fma_f32 v[102:103], v[68:69], v[204:205], v[102:103]
	v_pk_fma_f32 v[104:105], v[66:67], v[204:205], v[104:105]
	v_pk_fma_f32 v[106:107], v[64:65], v[204:205], v[106:107]
	v_pk_fma_f32 v[108:109], v[62:63], v[204:205], v[108:109]
	v_pk_fma_f32 v[110:111], v[60:61], v[204:205], v[110:111]
	s_waitcnt lgkmcnt(7)
	v_lshlrev_b32_e32 v204, 16, v185
	v_and_b32_e32 v205, 0xffff0000, v185
	v_pk_fma_f32 v[96:97], v[76:77], v[204:205], v[96:97]
	v_pk_fma_f32 v[98:99], v[74:75], v[204:205], v[98:99]
	v_pk_fma_f32 v[100:101], v[72:73], v[204:205], v[100:101]
	v_pk_fma_f32 v[102:103], v[70:71], v[204:205], v[102:103]
	v_pk_fma_f32 v[104:105], v[68:69], v[204:205], v[104:105]
	v_pk_fma_f32 v[106:107], v[66:67], v[204:205], v[106:107]
	v_pk_fma_f32 v[108:109], v[64:65], v[204:205], v[108:109]
	v_pk_fma_f32 v[110:111], v[62:63], v[204:205], v[110:111]
	s_waitcnt lgkmcnt(6)
	v_lshlrev_b32_e32 v204, 16, v186
	v_and_b32_e32 v205, 0xffff0000, v186
	v_pk_fma_f32 v[98:99], v[76:77], v[204:205], v[98:99]
	v_pk_fma_f32 v[100:101], v[74:75], v[204:205], v[100:101]
	v_pk_fma_f32 v[102:103], v[72:73], v[204:205], v[102:103]
	v_pk_fma_f32 v[104:105], v[70:71], v[204:205], v[104:105]
	v_pk_fma_f32 v[106:107], v[68:69], v[204:205], v[106:107]
	v_pk_fma_f32 v[108:109], v[66:67], v[204:205], v[108:109]
	v_pk_fma_f32 v[110:111], v[64:65], v[204:205], v[110:111]
	s_waitcnt lgkmcnt(5)
	v_lshlrev_b32_e32 v204, 16, v187
	v_and_b32_e32 v205, 0xffff0000, v187
	v_pk_fma_f32 v[100:101], v[76:77], v[204:205], v[100:101]
	v_pk_fma_f32 v[102:103], v[74:75], v[204:205], v[102:103]
	v_pk_fma_f32 v[104:105], v[72:73], v[204:205], v[104:105]
	v_pk_fma_f32 v[106:107], v[70:71], v[204:205], v[106:107]
	v_pk_fma_f32 v[108:109], v[68:69], v[204:205], v[108:109]
	v_pk_fma_f32 v[110:111], v[66:67], v[204:205], v[110:111]
	s_waitcnt lgkmcnt(4)
	v_lshlrev_b32_e32 v204, 16, v188
	v_and_b32_e32 v205, 0xffff0000, v188
	v_pk_fma_f32 v[102:103], v[76:77], v[204:205], v[102:103]
	v_pk_fma_f32 v[104:105], v[74:75], v[204:205], v[104:105]
	v_pk_fma_f32 v[106:107], v[72:73], v[204:205], v[106:107]
	v_pk_fma_f32 v[108:109], v[70:71], v[204:205], v[108:109]
	v_pk_fma_f32 v[110:111], v[68:69], v[204:205], v[110:111]
	s_waitcnt lgkmcnt(3)
	v_lshlrev_b32_e32 v204, 16, v189
	v_and_b32_e32 v205, 0xffff0000, v189
	v_pk_fma_f32 v[104:105], v[76:77], v[204:205], v[104:105]
	v_pk_fma_f32 v[106:107], v[74:75], v[204:205], v[106:107]
	v_pk_fma_f32 v[108:109], v[72:73], v[204:205], v[108:109]
	v_pk_fma_f32 v[110:111], v[70:71], v[204:205], v[110:111]
	s_waitcnt lgkmcnt(2)
	v_lshlrev_b32_e32 v204, 16, v190
	v_and_b32_e32 v205, 0xffff0000, v190
	v_pk_fma_f32 v[106:107], v[76:77], v[204:205], v[106:107]
	v_pk_fma_f32 v[108:109], v[74:75], v[204:205], v[108:109]
	v_pk_fma_f32 v[110:111], v[72:73], v[204:205], v[110:111]
	s_waitcnt lgkmcnt(1)
	v_lshlrev_b32_e32 v204, 16, v191
	v_and_b32_e32 v205, 0xffff0000, v191
	v_pk_fma_f32 v[108:109], v[76:77], v[204:205], v[108:109]
	v_pk_fma_f32 v[110:111], v[74:75], v[204:205], v[110:111]
	s_waitcnt lgkmcnt(0)
	v_lshlrev_b32_e32 v204, 16, v192
	v_and_b32_e32 v205, 0xffff0000, v192
	v_pk_fma_f32 v[110:111], v[76:77], v[204:205], v[110:111]
	ds_write_b64 v4, v[80:81] offset:0
	ds_write_b64 v4, v[82:83] offset:2048
	ds_write_b64 v4, v[84:85] offset:4096
	ds_write_b64 v4, v[86:87] offset:6144
	ds_write_b64 v4, v[88:89] offset:8192
	ds_write_b64 v4, v[90:91] offset:10240
	ds_write_b64 v4, v[92:93] offset:12288
	ds_write_b64 v4, v[94:95] offset:14336
	ds_write_b64 v4, v[96:97] offset:16384
	ds_write_b64 v4, v[98:99] offset:18432
	ds_write_b64 v4, v[100:101] offset:20480
	ds_write_b64 v4, v[102:103] offset:22528
	ds_write_b64 v4, v[104:105] offset:24576
	ds_write_b64 v4, v[106:107] offset:26624
	ds_write_b64 v4, v[108:109] offset:28672
	ds_write_b64 v4, v[110:111] offset:30720
	s_waitcnt lgkmcnt(0)
	s_barrier
	ds_read_b128 v[80:83], v5 offset:0
	ds_read_b128 v[84:87], v5 offset:16
	ds_read_b128 v[88:91], v5 offset:2048
	ds_read_b128 v[92:95], v5 offset:2064
	ds_read_b128 v[96:99], v5 offset:4096
	ds_read_b128 v[100:103], v5 offset:4112
	ds_read_b128 v[104:107], v5 offset:6144
	ds_read_b128 v[108:111], v5 offset:6160
	s_lshl_b32 s4, s12, 16
	s_lshl_b32 s5, s0, 13
	s_add_u32 s32, s10, s4
	s_addc_u32 s33, s11, 0
	s_add_u32 s32, s32, s5
	s_addc_u32 s33, s33, 0
	s_add_u32 s34, s32, 0x1000
	s_addc_u32 s35, s33, 0
	s_waitcnt lgkmcnt(0)
	v_add_f32_e32 v196, v80, v81
	v_add_f32_e32 v196, v196, v82
	v_add_f32_e32 v196, v196, v83
	v_add_f32_e32 v196, v196, v84
	v_add_f32_e32 v196, v196, v85
	v_add_f32_e32 v196, v196, v86
	v_add_f32_e32 v196, v196, v87
	v_add_f32_e32 v197, v88, v89
	v_add_f32_e32 v197, v197, v90
	v_add_f32_e32 v197, v197, v91
	v_add_f32_e32 v197, v197, v92
	v_add_f32_e32 v197, v197, v93
	v_add_f32_e32 v197, v197, v94
	v_add_f32_e32 v197, v197, v95
	v_add_f32_e32 v198, v96, v97
	v_add_f32_e32 v198, v198, v98
	v_add_f32_e32 v198, v198, v99
	v_add_f32_e32 v198, v198, v100
	v_add_f32_e32 v198, v198, v101
	v_add_f32_e32 v198, v198, v102
	v_add_f32_e32 v198, v198, v103
	v_add_f32_e32 v199, v104, v105
	v_add_f32_e32 v199, v199, v106
	v_add_f32_e32 v199, v199, v107
	v_add_f32_e32 v199, v199, v108
	v_add_f32_e32 v199, v199, v109
	v_add_f32_e32 v199, v199, v110
	v_add_f32_e32 v199, v199, v111
	v_add_f32_dpp v196, v196, v196 quad_perm:[1,0,3,2] row_mask:0xf bank_mask:0xf
	v_add_f32_dpp v197, v197, v197 quad_perm:[1,0,3,2] row_mask:0xf bank_mask:0xf
	v_add_f32_dpp v198, v198, v198 quad_perm:[1,0,3,2] row_mask:0xf bank_mask:0xf
	v_add_f32_dpp v199, v199, v199 quad_perm:[1,0,3,2] row_mask:0xf bank_mask:0xf
	v_add_f32_dpp v196, v196, v196 quad_perm:[2,3,0,1] row_mask:0xf bank_mask:0xf
	v_add_f32_dpp v197, v197, v197 quad_perm:[2,3,0,1] row_mask:0xf bank_mask:0xf
	v_add_f32_dpp v198, v198, v198 quad_perm:[2,3,0,1] row_mask:0xf bank_mask:0xf
	v_add_f32_dpp v199, v199, v199 quad_perm:[2,3,0,1] row_mask:0xf bank_mask:0xf
	v_add_f32_dpp v196, v196, v196 row_half_mirror row_mask:0xf bank_mask:0xf
	v_add_f32_dpp v197, v197, v197 row_half_mirror row_mask:0xf bank_mask:0xf
	v_add_f32_dpp v198, v198, v198 row_half_mirror row_mask:0xf bank_mask:0xf
	v_add_f32_dpp v199, v199, v199 row_half_mirror row_mask:0xf bank_mask:0xf
	v_add_f32_dpp v196, v196, v196 row_mirror row_mask:0xf bank_mask:0xf
	v_add_f32_dpp v197, v197, v197 row_mirror row_mask:0xf bank_mask:0xf
	v_add_f32_dpp v198, v198, v198 row_mirror row_mask:0xf bank_mask:0xf
	v_add_f32_dpp v199, v199, v199 row_mirror row_mask:0xf bank_mask:0xf
	v_add_f32_dpp v196, v196, v196 row_bcast:15 row_mask:0xa bank_mask:0xf
	v_add_f32_dpp v197, v197, v197 row_bcast:15 row_mask:0xa bank_mask:0xf
	v_add_f32_dpp v198, v198, v198 row_bcast:15 row_mask:0xa bank_mask:0xf
	v_add_f32_dpp v199, v199, v199 row_bcast:15 row_mask:0xa bank_mask:0xf
	v_add_f32_dpp v196, v196, v196 row_bcast:31 row_mask:0xc bank_mask:0xf
	v_add_f32_dpp v197, v197, v197 row_bcast:31 row_mask:0xc bank_mask:0xf
	v_add_f32_dpp v198, v198, v198 row_bcast:31 row_mask:0xc bank_mask:0xf
	v_add_f32_dpp v199, v199, v199 row_bcast:31 row_mask:0xc bank_mask:0xf
	v_readlane_b32 s24, v196, 63
	v_readlane_b32 s25, v197, 63
	v_readlane_b32 s26, v198, 63
	v_readlane_b32 s27, v199, 63
	s_nop 0
	v_mul_f32_e32 v200, s24, v8
	v_mul_f32_e32 v201, s25, v8
	v_mul_f32_e32 v202, s26, v8
	v_mul_f32_e32 v203, s27, v8
	v_sub_f32_e32 v80, v80, v200
	v_sub_f32_e32 v81, v81, v200
	v_sub_f32_e32 v82, v82, v200
	v_sub_f32_e32 v83, v83, v200
	v_sub_f32_e32 v84, v84, v200
	v_sub_f32_e32 v85, v85, v200
	v_sub_f32_e32 v86, v86, v200
	v_sub_f32_e32 v87, v87, v200
	v_sub_f32_e32 v88, v88, v201
	v_sub_f32_e32 v89, v89, v201
	v_sub_f32_e32 v90, v90, v201
	v_sub_f32_e32 v91, v91, v201
	v_sub_f32_e32 v92, v92, v201
	v_sub_f32_e32 v93, v93, v201
	v_sub_f32_e32 v94, v94, v201
	v_sub_f32_e32 v95, v95, v201
	v_sub_f32_e32 v96, v96, v202
	v_sub_f32_e32 v97, v97, v202
	v_sub_f32_e32 v98, v98, v202
	v_sub_f32_e32 v99, v99, v202
	v_sub_f32_e32 v100, v100, v202
	v_sub_f32_e32 v101, v101, v202
	v_sub_f32_e32 v102, v102, v202
	v_sub_f32_e32 v103, v103, v202
	v_sub_f32_e32 v104, v104, v203
	v_sub_f32_e32 v105, v105, v203
	v_sub_f32_e32 v106, v106, v203
	v_sub_f32_e32 v107, v107, v203
	v_sub_f32_e32 v108, v108, v203
	v_sub_f32_e32 v109, v109, v203
	v_sub_f32_e32 v110, v110, v203
	v_sub_f32_e32 v111, v111, v203
	v_mul_f32_e32 v196, v80, v80
	v_fmac_f32_e32 v196, v81, v81
	v_fmac_f32_e32 v196, v82, v82
	v_fmac_f32_e32 v196, v83, v83
	v_fmac_f32_e32 v196, v84, v84
	v_fmac_f32_e32 v196, v85, v85
	v_fmac_f32_e32 v196, v86, v86
	v_fmac_f32_e32 v196, v87, v87
	v_mul_f32_e32 v197, v88, v88
	v_fmac_f32_e32 v197, v89, v89
	v_fmac_f32_e32 v197, v90, v90
	v_fmac_f32_e32 v197, v91, v91
	v_fmac_f32_e32 v197, v92, v92
	v_fmac_f32_e32 v197, v93, v93
	v_fmac_f32_e32 v197, v94, v94
	v_fmac_f32_e32 v197, v95, v95
	v_mul_f32_e32 v198, v96, v96
	v_fmac_f32_e32 v198, v97, v97
	v_fmac_f32_e32 v198, v98, v98
	v_fmac_f32_e32 v198, v99, v99
	v_fmac_f32_e32 v198, v100, v100
	v_fmac_f32_e32 v198, v101, v101
	v_fmac_f32_e32 v198, v102, v102
	v_fmac_f32_e32 v198, v103, v103
	v_mul_f32_e32 v199, v104, v104
	v_fmac_f32_e32 v199, v105, v105
	v_fmac_f32_e32 v199, v106, v106
	v_fmac_f32_e32 v199, v107, v107
	v_fmac_f32_e32 v199, v108, v108
	v_fmac_f32_e32 v199, v109, v109
	v_fmac_f32_e32 v199, v110, v110
	v_fmac_f32_e32 v199, v111, v111
	v_add_f32_dpp v196, v196, v196 quad_perm:[1,0,3,2] row_mask:0xf bank_mask:0xf
	v_add_f32_dpp v197, v197, v197 quad_perm:[1,0,3,2] row_mask:0xf bank_mask:0xf
	v_add_f32_dpp v198, v198, v198 quad_perm:[1,0,3,2] row_mask:0xf bank_mask:0xf
	v_add_f32_dpp v199, v199, v199 quad_perm:[1,0,3,2] row_mask:0xf bank_mask:0xf
	v_add_f32_dpp v196, v196, v196 quad_perm:[2,3,0,1] row_mask:0xf bank_mask:0xf
	v_add_f32_dpp v197, v197, v197 quad_perm:[2,3,0,1] row_mask:0xf bank_mask:0xf
	v_add_f32_dpp v198, v198, v198 quad_perm:[2,3,0,1] row_mask:0xf bank_mask:0xf
	v_add_f32_dpp v199, v199, v199 quad_perm:[2,3,0,1] row_mask:0xf bank_mask:0xf
	v_add_f32_dpp v196, v196, v196 row_half_mirror row_mask:0xf bank_mask:0xf
	v_add_f32_dpp v197, v197, v197 row_half_mirror row_mask:0xf bank_mask:0xf
	v_add_f32_dpp v198, v198, v198 row_half_mirror row_mask:0xf bank_mask:0xf
	v_add_f32_dpp v199, v199, v199 row_half_mirror row_mask:0xf bank_mask:0xf
	v_add_f32_dpp v196, v196, v196 row_mirror row_mask:0xf bank_mask:0xf
	v_add_f32_dpp v197, v197, v197 row_mirror row_mask:0xf bank_mask:0xf
	v_add_f32_dpp v198, v198, v198 row_mirror row_mask:0xf bank_mask:0xf
	v_add_f32_dpp v199, v199, v199 row_mirror row_mask:0xf bank_mask:0xf
	v_add_f32_dpp v196, v196, v196 row_bcast:15 row_mask:0xa bank_mask:0xf
	v_add_f32_dpp v197, v197, v197 row_bcast:15 row_mask:0xa bank_mask:0xf
	v_add_f32_dpp v198, v198, v198 row_bcast:15 row_mask:0xa bank_mask:0xf
	v_add_f32_dpp v199, v199, v199 row_bcast:15 row_mask:0xa bank_mask:0xf
	v_add_f32_dpp v196, v196, v196 row_bcast:31 row_mask:0xc bank_mask:0xf
	v_add_f32_dpp v197, v197, v197 row_bcast:31 row_mask:0xc bank_mask:0xf
	v_add_f32_dpp v198, v198, v198 row_bcast:31 row_mask:0xc bank_mask:0xf
	v_add_f32_dpp v199, v199, v199 row_bcast:31 row_mask:0xc bank_mask:0xf
	v_readlane_b32 s24, v196, 63
	v_readlane_b32 s25, v197, 63
	v_readlane_b32 s26, v198, 63
	v_readlane_b32 s27, v199, 63
	s_nop 0
	v_fma_f32 v200, s24, v8, v9
	v_fma_f32 v201, s25, v8, v9
	v_fma_f32 v202, s26, v8, v9
	v_fma_f32 v203, s27, v8, v9
	v_rsq_f32_e32 v200, v200
	v_rsq_f32_e32 v201, v201
	v_rsq_f32_e32 v202, v202
	v_rsq_f32_e32 v203, v203
	s_nop 0
	v_mul_f32_e32 v80, v80, v200
	v_mul_f32_e32 v81, v81, v200
	v_mul_f32_e32 v82, v82, v200
	v_mul_f32_e32 v83, v83, v200
	v_mul_f32_e32 v84, v84, v200
	v_mul_f32_e32 v85, v85, v200
	v_mul_f32_e32 v86, v86, v200
	v_mul_f32_e32 v87, v87, v200
	v_fma_f32 v80, v80, v224, v232
	v_fma_f32 v81, v81, v225, v233
	v_fma_f32 v82, v82, v226, v234
	v_fma_f32 v83, v83, v227, v235
	v_fma_f32 v84, v84, v228, v236
	v_fma_f32 v85, v85, v229, v237
	v_fma_f32 v86, v86, v230, v238
	v_fma_f32 v87, v87, v231, v239
	v_mul_f32_e32 v88, v88, v201
	v_mul_f32_e32 v89, v89, v201
	v_mul_f32_e32 v90, v90, v201
	v_mul_f32_e32 v91, v91, v201
	v_mul_f32_e32 v92, v92, v201
	v_mul_f32_e32 v93, v93, v201
	v_mul_f32_e32 v94, v94, v201
	v_mul_f32_e32 v95, v95, v201
	v_fma_f32 v88, v88, v224, v232
	v_fma_f32 v89, v89, v225, v233
	v_fma_f32 v90, v90, v226, v234
	v_fma_f32 v91, v91, v227, v235
	v_fma_f32 v92, v92, v228, v236
	v_fma_f32 v93, v93, v229, v237
	v_fma_f32 v94, v94, v230, v238
	v_fma_f32 v95, v95, v231, v239
	v_mul_f32_e32 v96, v96, v202
	v_mul_f32_e32 v97, v97, v202
	v_mul_f32_e32 v98, v98, v202
	v_mul_f32_e32 v99, v99, v202
	v_mul_f32_e32 v100, v100, v202
	v_mul_f32_e32 v101, v101, v202
	v_mul_f32_e32 v102, v102, v202
	v_mul_f32_e32 v103, v103, v202
	v_fma_f32 v96, v96, v224, v232
	v_fma_f32 v97, v97, v225, v233
	v_fma_f32 v98, v98, v226, v234
	v_fma_f32 v99, v99, v227, v235
	v_fma_f32 v100, v100, v228, v236
	v_fma_f32 v101, v101, v229, v237
	v_fma_f32 v102, v102, v230, v238
	v_fma_f32 v103, v103, v231, v239
	v_mul_f32_e32 v104, v104, v203
	v_mul_f32_e32 v105, v105, v203
	v_mul_f32_e32 v106, v106, v203
	v_mul_f32_e32 v107, v107, v203
	v_mul_f32_e32 v108, v108, v203
	v_mul_f32_e32 v109, v109, v203
	v_mul_f32_e32 v110, v110, v203
	v_mul_f32_e32 v111, v111, v203
	v_fma_f32 v104, v104, v224, v232
	v_fma_f32 v105, v105, v225, v233
	v_fma_f32 v106, v106, v226, v234
	v_fma_f32 v107, v107, v227, v235
	v_fma_f32 v108, v108, v228, v236
	v_fma_f32 v109, v109, v229, v237
	v_fma_f32 v110, v110, v230, v238
	v_fma_f32 v111, v111, v231, v239
	v_mul_f32_e32 v160, v80, v11
	v_mul_f32_e32 v161, v81, v11
	v_mul_f32_e32 v162, v82, v11
	v_mul_f32_e32 v163, v83, v11
	v_mul_f32_e32 v164, v84, v11
	v_mul_f32_e32 v165, v85, v11
	v_mul_f32_e32 v166, v86, v11
	v_mul_f32_e32 v167, v87, v11
	v_exp_f32_e32 v160, v160
	v_exp_f32_e32 v161, v161
	v_exp_f32_e32 v162, v162
	v_exp_f32_e32 v163, v163
	v_exp_f32_e32 v164, v164
	v_exp_f32_e32 v165, v165
	v_exp_f32_e32 v166, v166
	v_exp_f32_e32 v167, v167
	s_nop 0
	v_add_f32_e32 v160, v160, v13
	v_add_f32_e32 v161, v161, v13
	v_add_f32_e32 v162, v162, v13
	v_add_f32_e32 v163, v163, v13
	v_add_f32_e32 v164, v164, v13
	v_add_f32_e32 v165, v165, v13
	v_add_f32_e32 v166, v166, v13
	v_add_f32_e32 v167, v167, v13
	v_rcp_f32_e32 v160, v160
	v_rcp_f32_e32 v161, v161
	v_rcp_f32_e32 v162, v162
	v_rcp_f32_e32 v163, v163
	v_rcp_f32_e32 v164, v164
	v_rcp_f32_e32 v165, v165
	v_rcp_f32_e32 v166, v166
	v_rcp_f32_e32 v167, v167
	s_nop 0
	v_mul_f32_e32 v80, v80, v160
	v_mul_f32_e32 v81, v81, v161
	v_mul_f32_e32 v82, v82, v162
	v_mul_f32_e32 v83, v83, v163
	v_mul_f32_e32 v84, v84, v164
	v_mul_f32_e32 v85, v85, v165
	v_mul_f32_e32 v86, v86, v166
	v_mul_f32_e32 v87, v87, v167
	v_cvt_pk_bf16_f32 v208, v80, v81
	v_cvt_pk_bf16_f32 v209, v82, v83
	v_cvt_pk_bf16_f32 v210, v84, v85
	v_cvt_pk_bf16_f32 v211, v86, v87
	global_store_dwordx4 v7, v[208:211], s[32:33] offset:0 nt
	v_mul_f32_e32 v160, v88, v11
	v_mul_f32_e32 v161, v89, v11
	v_mul_f32_e32 v162, v90, v11
	v_mul_f32_e32 v163, v91, v11
	v_mul_f32_e32 v164, v92, v11
	v_mul_f32_e32 v165, v93, v11
	v_mul_f32_e32 v166, v94, v11
	v_mul_f32_e32 v167, v95, v11
	v_exp_f32_e32 v160, v160
	v_exp_f32_e32 v161, v161
	v_exp_f32_e32 v162, v162
	v_exp_f32_e32 v163, v163
	v_exp_f32_e32 v164, v164
	v_exp_f32_e32 v165, v165
	v_exp_f32_e32 v166, v166
	v_exp_f32_e32 v167, v167
	s_nop 0
	v_add_f32_e32 v160, v160, v13
	v_add_f32_e32 v161, v161, v13
	v_add_f32_e32 v162, v162, v13
	v_add_f32_e32 v163, v163, v13
	v_add_f32_e32 v164, v164, v13
	v_add_f32_e32 v165, v165, v13
	v_add_f32_e32 v166, v166, v13
	v_add_f32_e32 v167, v167, v13
	v_rcp_f32_e32 v160, v160
	v_rcp_f32_e32 v161, v161
	v_rcp_f32_e32 v162, v162
	v_rcp_f32_e32 v163, v163
	v_rcp_f32_e32 v164, v164
	v_rcp_f32_e32 v165, v165
	v_rcp_f32_e32 v166, v166
	v_rcp_f32_e32 v167, v167
	s_nop 0
	v_mul_f32_e32 v88, v88, v160
	v_mul_f32_e32 v89, v89, v161
	v_mul_f32_e32 v90, v90, v162
	v_mul_f32_e32 v91, v91, v163
	v_mul_f32_e32 v92, v92, v164
	v_mul_f32_e32 v93, v93, v165
	v_mul_f32_e32 v94, v94, v166
	v_mul_f32_e32 v95, v95, v167
	v_cvt_pk_bf16_f32 v240, v88, v89
	v_cvt_pk_bf16_f32 v241, v90, v91
	v_cvt_pk_bf16_f32 v242, v92, v93
	v_cvt_pk_bf16_f32 v243, v94, v95
	global_store_dwordx4 v7, v[240:243], s[32:33] offset:2048 nt
	v_mul_f32_e32 v160, v96, v11
	v_mul_f32_e32 v161, v97, v11
	v_mul_f32_e32 v162, v98, v11
	v_mul_f32_e32 v163, v99, v11
	v_mul_f32_e32 v164, v100, v11
	v_mul_f32_e32 v165, v101, v11
	v_mul_f32_e32 v166, v102, v11
	v_mul_f32_e32 v167, v103, v11
	v_exp_f32_e32 v160, v160
	v_exp_f32_e32 v161, v161
	v_exp_f32_e32 v162, v162
	v_exp_f32_e32 v163, v163
	v_exp_f32_e32 v164, v164
	v_exp_f32_e32 v165, v165
	v_exp_f32_e32 v166, v166
	v_exp_f32_e32 v167, v167
	s_nop 0
	v_add_f32_e32 v160, v160, v13
	v_add_f32_e32 v161, v161, v13
	v_add_f32_e32 v162, v162, v13
	v_add_f32_e32 v163, v163, v13
	v_add_f32_e32 v164, v164, v13
	v_add_f32_e32 v165, v165, v13
	v_add_f32_e32 v166, v166, v13
	v_add_f32_e32 v167, v167, v13
	v_rcp_f32_e32 v160, v160
	v_rcp_f32_e32 v161, v161
	v_rcp_f32_e32 v162, v162
	v_rcp_f32_e32 v163, v163
	v_rcp_f32_e32 v164, v164
	v_rcp_f32_e32 v165, v165
	v_rcp_f32_e32 v166, v166
	v_rcp_f32_e32 v167, v167
	s_nop 0
	v_mul_f32_e32 v96, v96, v160
	v_mul_f32_e32 v97, v97, v161
	v_mul_f32_e32 v98, v98, v162
	v_mul_f32_e32 v99, v99, v163
	v_mul_f32_e32 v100, v100, v164
	v_mul_f32_e32 v101, v101, v165
	v_mul_f32_e32 v102, v102, v166
	v_mul_f32_e32 v103, v103, v167
	v_cvt_pk_bf16_f32 v148, v96, v97
	v_cvt_pk_bf16_f32 v149, v98, v99
	v_cvt_pk_bf16_f32 v150, v100, v101
	v_cvt_pk_bf16_f32 v151, v102, v103
	global_store_dwordx4 v7, v[148:151], s[34:35] offset:0 nt
	v_mul_f32_e32 v160, v104, v11
	v_mul_f32_e32 v161, v105, v11
	v_mul_f32_e32 v162, v106, v11
	v_mul_f32_e32 v163, v107, v11
	v_mul_f32_e32 v164, v108, v11
	v_mul_f32_e32 v165, v109, v11
	v_mul_f32_e32 v166, v110, v11
	v_mul_f32_e32 v167, v111, v11
	v_exp_f32_e32 v160, v160
	v_exp_f32_e32 v161, v161
	v_exp_f32_e32 v162, v162
	v_exp_f32_e32 v163, v163
	v_exp_f32_e32 v164, v164
	v_exp_f32_e32 v165, v165
	v_exp_f32_e32 v166, v166
	v_exp_f32_e32 v167, v167
	s_nop 0
	v_add_f32_e32 v160, v160, v13
	v_add_f32_e32 v161, v161, v13
	v_add_f32_e32 v162, v162, v13
	v_add_f32_e32 v163, v163, v13
	v_add_f32_e32 v164, v164, v13
	v_add_f32_e32 v165, v165, v13
	v_add_f32_e32 v166, v166, v13
	v_add_f32_e32 v167, v167, v13
	v_rcp_f32_e32 v160, v160
	v_rcp_f32_e32 v161, v161
	v_rcp_f32_e32 v162, v162
	v_rcp_f32_e32 v163, v163
	v_rcp_f32_e32 v164, v164
	v_rcp_f32_e32 v165, v165
	v_rcp_f32_e32 v166, v166
	v_rcp_f32_e32 v167, v167
	s_nop 0
	v_mul_f32_e32 v104, v104, v160
	v_mul_f32_e32 v105, v105, v161
	v_mul_f32_e32 v106, v106, v162
	v_mul_f32_e32 v107, v107, v163
	v_mul_f32_e32 v108, v108, v164
	v_mul_f32_e32 v109, v109, v165
	v_mul_f32_e32 v110, v110, v166
	v_mul_f32_e32 v111, v111, v167
	v_cvt_pk_bf16_f32 v152, v104, v105
	v_cvt_pk_bf16_f32 v153, v106, v107
	v_cvt_pk_bf16_f32 v154, v108, v109
	v_cvt_pk_bf16_f32 v155, v110, v111
	global_store_dwordx4 v7, v[152:155], s[34:35] offset:2048 nt
	s_add_i32 s12, s12, s66
	s_cmp_lt_i32 s12, 0x400
	s_cbranch_scc1 .Lcv_loop

.Lgm_loop:
	v_lshlrev_b32_e32 v4, 5, v0
	global_load_dwordx4 v[112:115], v4, s[8:9]
	global_load_dwordx4 v[116:119], v4, s[8:9] offset:16
	global_load_dwordx4 v[120:123], v4, s[10:11]
	global_load_dwordx4 v[124:127], v4, s[10:11] offset:16
	s_lshl_b32 s4, s1, 7
	s_lshl_b32 s5, s0, 4
	s_add_i32 s4, s4, s5
	s_mul_i32 s5, s4, 0x1400
	s_add_u32 s34, s28, s5
	s_addc_u32 s35, s29, 0
	s_add_u32 s34, s34, 0x1000
	s_addc_u32 s35, s35, 0
	s_add_u32 s36, s34, 0x1400
	s_addc_u32 s37, s35, 0
	global_load_dwordx4 v[8:11], v6, s[34:35]
	s_add_u32 s34, s34, 0x2800
	s_addc_u32 s35, s35, 0
	global_load_dwordx4 v[12:15], v6, s[36:37]
	s_add_u32 s36, s36, 0x2800
	s_addc_u32 s37, s37, 0
	global_load_dwordx4 v[16:19], v6, s[34:35]
	s_add_u32 s34, s34, 0x2800
	s_addc_u32 s35, s35, 0
	global_load_dwordx4 v[20:23], v6, s[36:37]
	s_add_u32 s36, s36, 0x2800
	s_addc_u32 s37, s37, 0
	global_load_dwordx4 v[24:27], v6, s[34:35]
	s_add_u32 s34, s34, 0x2800
	s_addc_u32 s35, s35, 0
	global_load_dwordx4 v[28:31], v6, s[36:37]
	s_add_u32 s36, s36, 0x2800
	s_addc_u32 s37, s37, 0
	global_load_dwordx4 v[32:35], v6, s[34:35]
	s_add_u32 s34, s34, 0x2800
	s_addc_u32 s35, s35, 0
	global_load_dwordx4 v[36:39], v6, s[36:37]
	s_add_u32 s36, s36, 0x2800
	s_addc_u32 s37, s37, 0
	global_load_dwordx4 v[40:43], v6, s[34:35]
	s_add_u32 s34, s34, 0x2800
	s_addc_u32 s35, s35, 0
	global_load_dwordx4 v[44:47], v6, s[36:37]
	s_add_u32 s36, s36, 0x2800
	s_addc_u32 s37, s37, 0
	global_load_dwordx4 v[48:51], v6, s[34:35]
	s_add_u32 s34, s34, 0x2800
	s_addc_u32 s35, s35, 0
	global_load_dwordx4 v[52:55], v6, s[36:37]
	s_add_u32 s36, s36, 0x2800
	s_addc_u32 s37, s37, 0
	global_load_dwordx4 v[56:59], v6, s[34:35]
	s_add_u32 s34, s34, 0x2800
	s_addc_u32 s35, s35, 0
	global_load_dwordx4 v[60:63], v6, s[36:37]
	s_add_u32 s36, s36, 0x2800
	s_addc_u32 s37, s37, 0
	global_load_dwordx4 v[64:67], v6, s[34:35]
	global_load_dwordx4 v[68:71], v6, s[36:37]
	s_lshl_b32 s4, s1, 7
	s_mul_i32 s4, s4, 0x1400
	s_lshl_b32 s5, s0, 7
	s_add_i32 s5, s5, 0xc00
	s_add_u32 s34, s28, s4
	s_addc_u32 s35, s29, 0
	s_add_u32 s34, s34, s5
	s_addc_u32 s35, s35, 0
	s_add_u32 s36, s34, 0x28000
	s_addc_u32 s37, s35, 0
	global_load_dwordx4 v[144:147], v138, s[34:35] offset:0
	global_load_dwordx4 v[148:151], v138, s[34:35] offset:32
	global_load_dwordx4 v[152:155], v138, s[34:35] offset:64
	global_load_dwordx4 v[156:159], v138, s[34:35] offset:96
	s_add_u32 s34, s34, 0x50000
	s_addc_u32 s35, s35, 0
	global_load_dwordx4 v[160:163], v138, s[36:37] offset:0
	global_load_dwordx4 v[164:167], v138, s[36:37] offset:32
	global_load_dwordx4 v[168:171], v138, s[36:37] offset:64
	global_load_dwordx4 v[172:175], v138, s[36:37] offset:96
	s_add_u32 s36, s36, 0x50000
	s_addc_u32 s37, s37, 0
	global_load_dwordx4 v[176:179], v138, s[34:35] offset:0
	global_load_dwordx4 v[184:187], v138, s[34:35] offset:32
	global_load_dwordx4 v[188:191], v138, s[34:35] offset:64
	global_load_dwordx4 v[192:195], v138, s[34:35] offset:96
	global_load_dwordx4 v[196:199], v138, s[36:37] offset:0
	global_load_dwordx4 v[200:203], v138, s[36:37] offset:32
	global_load_dwordx4 v[204:207], v138, s[36:37] offset:64
	global_load_dwordx4 v[240:243], v138, s[36:37] offset:96
	s_waitcnt vmcnt(28)
	v_lshlrev_b32_e32 v72, 16, v8
	v_and_b32_e32 v73, 0xffff0000, v8
	v_lshlrev_b32_e32 v74, 16, v9
	v_and_b32_e32 v75, 0xffff0000, v9
	v_lshlrev_b32_e32 v76, 16, v10
	v_and_b32_e32 v77, 0xffff0000, v10
	v_lshlrev_b32_e32 v78, 16, v11
	v_and_b32_e32 v79, 0xffff0000, v11
	v_lshlrev_b32_e32 v80, 16, v12
	v_and_b32_e32 v81, 0xffff0000, v12
	v_lshlrev_b32_e32 v82, 16, v13
	v_and_b32_e32 v83, 0xffff0000, v13
	v_lshlrev_b32_e32 v84, 16, v14
	v_and_b32_e32 v85, 0xffff0000, v14
	v_lshlrev_b32_e32 v86, 16, v15
	v_and_b32_e32 v87, 0xffff0000, v15
	v_lshlrev_b32_e32 v88, 16, v16
	v_and_b32_e32 v89, 0xffff0000, v16
	v_lshlrev_b32_e32 v90, 16, v17
	v_and_b32_e32 v91, 0xffff0000, v17
	v_lshlrev_b32_e32 v92, 16, v18
	v_and_b32_e32 v93, 0xffff0000, v18
	v_lshlrev_b32_e32 v94, 16, v19
	v_and_b32_e32 v95, 0xffff0000, v19
	v_lshlrev_b32_e32 v96, 16, v20
	v_and_b32_e32 v97, 0xffff0000, v20
	v_lshlrev_b32_e32 v98, 16, v21
	v_and_b32_e32 v99, 0xffff0000, v21
	v_lshlrev_b32_e32 v100, 16, v22
	v_and_b32_e32 v101, 0xffff0000, v22
	v_lshlrev_b32_e32 v102, 16, v23
	v_and_b32_e32 v103, 0xffff0000, v23
	v_add_f32_e32 v104, v72, v73
	v_add_f32_e32 v104, v104, v74
	v_add_f32_e32 v104, v104, v75
	v_add_f32_e32 v104, v104, v76
	v_add_f32_e32 v104, v104, v77
	v_add_f32_e32 v104, v104, v78
	v_add_f32_e32 v104, v104, v79
	v_add_f32_e32 v105, v80, v81
	v_add_f32_e32 v105, v105, v82
	v_add_f32_e32 v105, v105, v83
	v_add_f32_e32 v105, v105, v84
	v_add_f32_e32 v105, v105, v85
	v_add_f32_e32 v105, v105, v86
	v_add_f32_e32 v105, v105, v87
	v_add_f32_e32 v106, v88, v89
	v_add_f32_e32 v106, v106, v90
	v_add_f32_e32 v106, v106, v91
	v_add_f32_e32 v106, v106, v92
	v_add_f32_e32 v106, v106, v93
	v_add_f32_e32 v106, v106, v94
	v_add_f32_e32 v106, v106, v95
	v_add_f32_e32 v107, v96, v97
	v_add_f32_e32 v107, v107, v98
	v_add_f32_e32 v107, v107, v99
	v_add_f32_e32 v107, v107, v100
	v_add_f32_e32 v107, v107, v101
	v_add_f32_e32 v107, v107, v102
	v_add_f32_e32 v107, v107, v103
	v_add_f32_dpp v104, v104, v104 quad_perm:[1,0,3,2] row_mask:0xf bank_mask:0xf
	v_add_f32_dpp v105, v105, v105 quad_perm:[1,0,3,2] row_mask:0xf bank_mask:0xf
	v_add_f32_dpp v106, v106, v106 quad_perm:[1,0,3,2] row_mask:0xf bank_mask:0xf
	v_add_f32_dpp v107, v107, v107 quad_perm:[1,0,3,2] row_mask:0xf bank_mask:0xf
	v_add_f32_dpp v104, v104, v104 quad_perm:[2,3,0,1] row_mask:0xf bank_mask:0xf
	v_add_f32_dpp v105, v105, v105 quad_perm:[2,3,0,1] row_mask:0xf bank_mask:0xf
	v_add_f32_dpp v106, v106, v106 quad_perm:[2,3,0,1] row_mask:0xf bank_mask:0xf
	v_add_f32_dpp v107, v107, v107 quad_perm:[2,3,0,1] row_mask:0xf bank_mask:0xf
	v_add_f32_dpp v104, v104, v104 row_half_mirror row_mask:0xf bank_mask:0xf
	v_add_f32_dpp v105, v105, v105 row_half_mirror row_mask:0xf bank_mask:0xf
	v_add_f32_dpp v106, v106, v106 row_half_mirror row_mask:0xf bank_mask:0xf
	v_add_f32_dpp v107, v107, v107 row_half_mirror row_mask:0xf bank_mask:0xf
	v_add_f32_dpp v104, v104, v104 row_mirror row_mask:0xf bank_mask:0xf
	v_add_f32_dpp v105, v105, v105 row_mirror row_mask:0xf bank_mask:0xf
	v_add_f32_dpp v106, v106, v106 row_mirror row_mask:0xf bank_mask:0xf
	v_add_f32_dpp v107, v107, v107 row_mirror row_mask:0xf bank_mask:0xf
	v_add_f32_dpp v104, v104, v104 row_bcast:15 row_mask:0xa bank_mask:0xf
	v_add_f32_dpp v105, v105, v105 row_bcast:15 row_mask:0xa bank_mask:0xf
	v_add_f32_dpp v106, v106, v106 row_bcast:15 row_mask:0xa bank_mask:0xf
	v_add_f32_dpp v107, v107, v107 row_bcast:15 row_mask:0xa bank_mask:0xf
	v_add_f32_dpp v104, v104, v104 row_bcast:31 row_mask:0xc bank_mask:0xf
	v_add_f32_dpp v105, v105, v105 row_bcast:31 row_mask:0xc bank_mask:0xf
	v_add_f32_dpp v106, v106, v106 row_bcast:31 row_mask:0xc bank_mask:0xf
	v_add_f32_dpp v107, v107, v107 row_bcast:31 row_mask:0xc bank_mask:0xf
	v_readlane_b32 s24, v104, 63
	v_readlane_b32 s25, v105, 63
	v_readlane_b32 s26, v106, 63
	v_readlane_b32 s27, v107, 63
	s_nop 0
	v_mul_f32_e32 v108, s24, v7
	v_mul_f32_e32 v109, s25, v7
	v_mul_f32_e32 v110, s26, v7
	v_mul_f32_e32 v111, s27, v7
	v_sub_f32_e32 v72, v72, v108
	v_sub_f32_e32 v73, v73, v108
	v_sub_f32_e32 v74, v74, v108
	v_sub_f32_e32 v75, v75, v108
	v_sub_f32_e32 v76, v76, v108
	v_sub_f32_e32 v77, v77, v108
	v_sub_f32_e32 v78, v78, v108
	v_sub_f32_e32 v79, v79, v108
	v_sub_f32_e32 v80, v80, v109
	v_sub_f32_e32 v81, v81, v109
	v_sub_f32_e32 v82, v82, v109
	v_sub_f32_e32 v83, v83, v109
	v_sub_f32_e32 v84, v84, v109
	v_sub_f32_e32 v85, v85, v109
	v_sub_f32_e32 v86, v86, v109
	v_sub_f32_e32 v87, v87, v109
	v_sub_f32_e32 v88, v88, v110
	v_sub_f32_e32 v89, v89, v110
	v_sub_f32_e32 v90, v90, v110
	v_sub_f32_e32 v91, v91, v110
	v_sub_f32_e32 v92, v92, v110
	v_sub_f32_e32 v93, v93, v110
	v_sub_f32_e32 v94, v94, v110
	v_sub_f32_e32 v95, v95, v110
	v_sub_f32_e32 v96, v96, v111
	v_sub_f32_e32 v97, v97, v111
	v_sub_f32_e32 v98, v98, v111
	v_sub_f32_e32 v99, v99, v111
	v_sub_f32_e32 v100, v100, v111
	v_sub_f32_e32 v101, v101, v111
	v_sub_f32_e32 v102, v102, v111
	v_sub_f32_e32 v103, v103, v111
	v_mul_f32_e32 v104, v72, v72
	v_fmac_f32_e32 v104, v73, v73
	v_fmac_f32_e32 v104, v74, v74
	v_fmac_f32_e32 v104, v75, v75
	v_fmac_f32_e32 v104, v76, v76
	v_fmac_f32_e32 v104, v77, v77
	v_fmac_f32_e32 v104, v78, v78
	v_fmac_f32_e32 v104, v79, v79
	v_mul_f32_e32 v105, v80, v80
	v_fmac_f32_e32 v105, v81, v81
	v_fmac_f32_e32 v105, v82, v82
	v_fmac_f32_e32 v105, v83, v83
	v_fmac_f32_e32 v105, v84, v84
	v_fmac_f32_e32 v105, v85, v85
	v_fmac_f32_e32 v105, v86, v86
	v_fmac_f32_e32 v105, v87, v87
	v_mul_f32_e32 v106, v88, v88
	v_fmac_f32_e32 v106, v89, v89
	v_fmac_f32_e32 v106, v90, v90
	v_fmac_f32_e32 v106, v91, v91
	v_fmac_f32_e32 v106, v92, v92
	v_fmac_f32_e32 v106, v93, v93
	v_fmac_f32_e32 v106, v94, v94
	v_fmac_f32_e32 v106, v95, v95
	v_mul_f32_e32 v107, v96, v96
	v_fmac_f32_e32 v107, v97, v97
	v_fmac_f32_e32 v107, v98, v98
	v_fmac_f32_e32 v107, v99, v99
	v_fmac_f32_e32 v107, v100, v100
	v_fmac_f32_e32 v107, v101, v101
	v_fmac_f32_e32 v107, v102, v102
	v_fmac_f32_e32 v107, v103, v103
	v_add_f32_dpp v104, v104, v104 quad_perm:[1,0,3,2] row_mask:0xf bank_mask:0xf
	v_add_f32_dpp v105, v105, v105 quad_perm:[1,0,3,2] row_mask:0xf bank_mask:0xf
	v_add_f32_dpp v106, v106, v106 quad_perm:[1,0,3,2] row_mask:0xf bank_mask:0xf
	v_add_f32_dpp v107, v107, v107 quad_perm:[1,0,3,2] row_mask:0xf bank_mask:0xf
	v_add_f32_dpp v104, v104, v104 quad_perm:[2,3,0,1] row_mask:0xf bank_mask:0xf
	v_add_f32_dpp v105, v105, v105 quad_perm:[2,3,0,1] row_mask:0xf bank_mask:0xf
	v_add_f32_dpp v106, v106, v106 quad_perm:[2,3,0,1] row_mask:0xf bank_mask:0xf
	v_add_f32_dpp v107, v107, v107 quad_perm:[2,3,0,1] row_mask:0xf bank_mask:0xf
	v_add_f32_dpp v104, v104, v104 row_half_mirror row_mask:0xf bank_mask:0xf
	v_add_f32_dpp v105, v105, v105 row_half_mirror row_mask:0xf bank_mask:0xf
	v_add_f32_dpp v106, v106, v106 row_half_mirror row_mask:0xf bank_mask:0xf
	v_add_f32_dpp v107, v107, v107 row_half_mirror row_mask:0xf bank_mask:0xf
	v_add_f32_dpp v104, v104, v104 row_mirror row_mask:0xf bank_mask:0xf
	v_add_f32_dpp v105, v105, v105 row_mirror row_mask:0xf bank_mask:0xf
	v_add_f32_dpp v106, v106, v106 row_mirror row_mask:0xf bank_mask:0xf
	v_add_f32_dpp v107, v107, v107 row_mirror row_mask:0xf bank_mask:0xf
	v_add_f32_dpp v104, v104, v104 row_bcast:15 row_mask:0xa bank_mask:0xf
	v_add_f32_dpp v105, v105, v105 row_bcast:15 row_mask:0xa bank_mask:0xf
	v_add_f32_dpp v106, v106, v106 row_bcast:15 row_mask:0xa bank_mask:0xf
	v_add_f32_dpp v107, v107, v107 row_bcast:15 row_mask:0xa bank_mask:0xf
	v_add_f32_dpp v104, v104, v104 row_bcast:31 row_mask:0xc bank_mask:0xf
	v_add_f32_dpp v105, v105, v105 row_bcast:31 row_mask:0xc bank_mask:0xf
	v_add_f32_dpp v106, v106, v106 row_bcast:31 row_mask:0xc bank_mask:0xf
	v_add_f32_dpp v107, v107, v107 row_bcast:31 row_mask:0xc bank_mask:0xf
	v_readlane_b32 s24, v104, 63
	v_readlane_b32 s25, v105, 63
	v_readlane_b32 s26, v106, 63
	v_readlane_b32 s27, v107, 63
	s_nop 0
	v_fma_f32 v108, s24, v7, v132
	v_fma_f32 v109, s25, v7, v132
	v_fma_f32 v110, s26, v7, v132
	v_fma_f32 v111, s27, v7, v132
	v_rsq_f32_e32 v108, v108
	v_rsq_f32_e32 v109, v109
	v_rsq_f32_e32 v110, v110
	v_rsq_f32_e32 v111, v111
	s_nop 0
	v_mul_f32_e32 v72, v72, v108
	v_mul_f32_e32 v73, v73, v108
	v_mul_f32_e32 v74, v74, v108
	v_mul_f32_e32 v75, v75, v108
	v_mul_f32_e32 v76, v76, v108
	v_mul_f32_e32 v77, v77, v108
	v_mul_f32_e32 v78, v78, v108
	v_mul_f32_e32 v79, v79, v108
	v_fma_f32 v72, v72, v112, v120
	v_fma_f32 v73, v73, v113, v121
	v_fma_f32 v74, v74, v114, v122
	v_fma_f32 v75, v75, v115, v123
	v_fma_f32 v76, v76, v116, v124
	v_fma_f32 v77, v77, v117, v125
	v_fma_f32 v78, v78, v118, v126
	v_fma_f32 v79, v79, v119, v127
	v_mul_f32_e32 v80, v80, v109
	v_mul_f32_e32 v81, v81, v109
	v_mul_f32_e32 v82, v82, v109
	v_mul_f32_e32 v83, v83, v109
	v_mul_f32_e32 v84, v84, v109
	v_mul_f32_e32 v85, v85, v109
	v_mul_f32_e32 v86, v86, v109
	v_mul_f32_e32 v87, v87, v109
	v_fma_f32 v80, v80, v112, v120
	v_fma_f32 v81, v81, v113, v121
	v_fma_f32 v82, v82, v114, v122
	v_fma_f32 v83, v83, v115, v123
	v_fma_f32 v84, v84, v116, v124
	v_fma_f32 v85, v85, v117, v125
	v_fma_f32 v86, v86, v118, v126
	v_fma_f32 v87, v87, v119, v127
	v_mul_f32_e32 v88, v88, v110
	v_mul_f32_e32 v89, v89, v110
	v_mul_f32_e32 v90, v90, v110
	v_mul_f32_e32 v91, v91, v110
	v_mul_f32_e32 v92, v92, v110
	v_mul_f32_e32 v93, v93, v110
	v_mul_f32_e32 v94, v94, v110
	v_mul_f32_e32 v95, v95, v110
	v_fma_f32 v88, v88, v112, v120
	v_fma_f32 v89, v89, v113, v121
	v_fma_f32 v90, v90, v114, v122
	v_fma_f32 v91, v91, v115, v123
	v_fma_f32 v92, v92, v116, v124
	v_fma_f32 v93, v93, v117, v125
	v_fma_f32 v94, v94, v118, v126
	v_fma_f32 v95, v95, v119, v127
	v_mul_f32_e32 v96, v96, v111
	v_mul_f32_e32 v97, v97, v111
	v_mul_f32_e32 v98, v98, v111
	v_mul_f32_e32 v99, v99, v111
	v_mul_f32_e32 v100, v100, v111
	v_mul_f32_e32 v101, v101, v111
	v_mul_f32_e32 v102, v102, v111
	v_mul_f32_e32 v103, v103, v111
	v_fma_f32 v96, v96, v112, v120
	v_fma_f32 v97, v97, v113, v121
	v_fma_f32 v98, v98, v114, v122
	v_fma_f32 v99, v99, v115, v123
	v_fma_f32 v100, v100, v116, v124
	v_fma_f32 v101, v101, v117, v125
	v_fma_f32 v102, v102, v118, v126
	v_fma_f32 v103, v103, v119, v127
	v_cvt_pk_bf16_f32 v8, v72, v73
	v_cvt_pk_bf16_f32 v9, v74, v75
	v_cvt_pk_bf16_f32 v10, v76, v77
	v_cvt_pk_bf16_f32 v11, v78, v79
	v_cvt_pk_bf16_f32 v12, v80, v81
	v_cvt_pk_bf16_f32 v13, v82, v83
	v_cvt_pk_bf16_f32 v14, v84, v85
	v_cvt_pk_bf16_f32 v15, v86, v87
	v_cvt_pk_bf16_f32 v16, v88, v89
	v_cvt_pk_bf16_f32 v17, v90, v91
	v_cvt_pk_bf16_f32 v18, v92, v93
	v_cvt_pk_bf16_f32 v19, v94, v95
	v_cvt_pk_bf16_f32 v20, v96, v97
	v_cvt_pk_bf16_f32 v21, v98, v99
	v_cvt_pk_bf16_f32 v22, v100, v101
	v_cvt_pk_bf16_f32 v23, v102, v103
	ds_write_b128 v128, v[8:11] offset:0
	ds_write_b128 v129, v[12:15] offset:1024
	ds_write_b128 v130, v[16:19] offset:2048
	ds_write_b128 v131, v[20:23] offset:3072
	s_waitcnt vmcnt(24)
	v_lshlrev_b32_e32 v72, 16, v24
	v_and_b32_e32 v73, 0xffff0000, v24
	v_lshlrev_b32_e32 v74, 16, v25
	v_and_b32_e32 v75, 0xffff0000, v25
	v_lshlrev_b32_e32 v76, 16, v26
	v_and_b32_e32 v77, 0xffff0000, v26
	v_lshlrev_b32_e32 v78, 16, v27
	v_and_b32_e32 v79, 0xffff0000, v27
	v_lshlrev_b32_e32 v80, 16, v28
	v_and_b32_e32 v81, 0xffff0000, v28
	v_lshlrev_b32_e32 v82, 16, v29
	v_and_b32_e32 v83, 0xffff0000, v29
	v_lshlrev_b32_e32 v84, 16, v30
	v_and_b32_e32 v85, 0xffff0000, v30
	v_lshlrev_b32_e32 v86, 16, v31
	v_and_b32_e32 v87, 0xffff0000, v31
	v_lshlrev_b32_e32 v88, 16, v32
	v_and_b32_e32 v89, 0xffff0000, v32
	v_lshlrev_b32_e32 v90, 16, v33
	v_and_b32_e32 v91, 0xffff0000, v33
	v_lshlrev_b32_e32 v92, 16, v34
	v_and_b32_e32 v93, 0xffff0000, v34
	v_lshlrev_b32_e32 v94, 16, v35
	v_and_b32_e32 v95, 0xffff0000, v35
	v_lshlrev_b32_e32 v96, 16, v36
	v_and_b32_e32 v97, 0xffff0000, v36
	v_lshlrev_b32_e32 v98, 16, v37
	v_and_b32_e32 v99, 0xffff0000, v37
	v_lshlrev_b32_e32 v100, 16, v38
	v_and_b32_e32 v101, 0xffff0000, v38
	v_lshlrev_b32_e32 v102, 16, v39
	v_and_b32_e32 v103, 0xffff0000, v39
	v_add_f32_e32 v104, v72, v73
	v_add_f32_e32 v104, v104, v74
	v_add_f32_e32 v104, v104, v75
	v_add_f32_e32 v104, v104, v76
	v_add_f32_e32 v104, v104, v77
	v_add_f32_e32 v104, v104, v78
	v_add_f32_e32 v104, v104, v79
	v_add_f32_e32 v105, v80, v81
	v_add_f32_e32 v105, v105, v82
	v_add_f32_e32 v105, v105, v83
	v_add_f32_e32 v105, v105, v84
	v_add_f32_e32 v105, v105, v85
	v_add_f32_e32 v105, v105, v86
	v_add_f32_e32 v105, v105, v87
	v_add_f32_e32 v106, v88, v89
	v_add_f32_e32 v106, v106, v90
	v_add_f32_e32 v106, v106, v91
	v_add_f32_e32 v106, v106, v92
	v_add_f32_e32 v106, v106, v93
	v_add_f32_e32 v106, v106, v94
	v_add_f32_e32 v106, v106, v95
	v_add_f32_e32 v107, v96, v97
	v_add_f32_e32 v107, v107, v98
	v_add_f32_e32 v107, v107, v99
	v_add_f32_e32 v107, v107, v100
	v_add_f32_e32 v107, v107, v101
	v_add_f32_e32 v107, v107, v102
	v_add_f32_e32 v107, v107, v103
	v_add_f32_dpp v104, v104, v104 quad_perm:[1,0,3,2] row_mask:0xf bank_mask:0xf
	v_add_f32_dpp v105, v105, v105 quad_perm:[1,0,3,2] row_mask:0xf bank_mask:0xf
	v_add_f32_dpp v106, v106, v106 quad_perm:[1,0,3,2] row_mask:0xf bank_mask:0xf
	v_add_f32_dpp v107, v107, v107 quad_perm:[1,0,3,2] row_mask:0xf bank_mask:0xf
	v_add_f32_dpp v104, v104, v104 quad_perm:[2,3,0,1] row_mask:0xf bank_mask:0xf
	v_add_f32_dpp v105, v105, v105 quad_perm:[2,3,0,1] row_mask:0xf bank_mask:0xf
	v_add_f32_dpp v106, v106, v106 quad_perm:[2,3,0,1] row_mask:0xf bank_mask:0xf
	v_add_f32_dpp v107, v107, v107 quad_perm:[2,3,0,1] row_mask:0xf bank_mask:0xf
	v_add_f32_dpp v104, v104, v104 row_half_mirror row_mask:0xf bank_mask:0xf
	v_add_f32_dpp v105, v105, v105 row_half_mirror row_mask:0xf bank_mask:0xf
	v_add_f32_dpp v106, v106, v106 row_half_mirror row_mask:0xf bank_mask:0xf
	v_add_f32_dpp v107, v107, v107 row_half_mirror row_mask:0xf bank_mask:0xf
	v_add_f32_dpp v104, v104, v104 row_mirror row_mask:0xf bank_mask:0xf
	v_add_f32_dpp v105, v105, v105 row_mirror row_mask:0xf bank_mask:0xf
	v_add_f32_dpp v106, v106, v106 row_mirror row_mask:0xf bank_mask:0xf
	v_add_f32_dpp v107, v107, v107 row_mirror row_mask:0xf bank_mask:0xf
	v_add_f32_dpp v104, v104, v104 row_bcast:15 row_mask:0xa bank_mask:0xf
	v_add_f32_dpp v105, v105, v105 row_bcast:15 row_mask:0xa bank_mask:0xf
	v_add_f32_dpp v106, v106, v106 row_bcast:15 row_mask:0xa bank_mask:0xf
	v_add_f32_dpp v107, v107, v107 row_bcast:15 row_mask:0xa bank_mask:0xf
	v_add_f32_dpp v104, v104, v104 row_bcast:31 row_mask:0xc bank_mask:0xf
	v_add_f32_dpp v105, v105, v105 row_bcast:31 row_mask:0xc bank_mask:0xf
	v_add_f32_dpp v106, v106, v106 row_bcast:31 row_mask:0xc bank_mask:0xf
	v_add_f32_dpp v107, v107, v107 row_bcast:31 row_mask:0xc bank_mask:0xf
	v_readlane_b32 s24, v104, 63
	v_readlane_b32 s25, v105, 63
	v_readlane_b32 s26, v106, 63
	v_readlane_b32 s27, v107, 63
	s_nop 0
	v_mul_f32_e32 v108, s24, v7
	v_mul_f32_e32 v109, s25, v7
	v_mul_f32_e32 v110, s26, v7
	v_mul_f32_e32 v111, s27, v7
	v_sub_f32_e32 v72, v72, v108
	v_sub_f32_e32 v73, v73, v108
	v_sub_f32_e32 v74, v74, v108
	v_sub_f32_e32 v75, v75, v108
	v_sub_f32_e32 v76, v76, v108
	v_sub_f32_e32 v77, v77, v108
	v_sub_f32_e32 v78, v78, v108
	v_sub_f32_e32 v79, v79, v108
	v_sub_f32_e32 v80, v80, v109
	v_sub_f32_e32 v81, v81, v109
	v_sub_f32_e32 v82, v82, v109
	v_sub_f32_e32 v83, v83, v109
	v_sub_f32_e32 v84, v84, v109
	v_sub_f32_e32 v85, v85, v109
	v_sub_f32_e32 v86, v86, v109
	v_sub_f32_e32 v87, v87, v109
	v_sub_f32_e32 v88, v88, v110
	v_sub_f32_e32 v89, v89, v110
	v_sub_f32_e32 v90, v90, v110
	v_sub_f32_e32 v91, v91, v110
	v_sub_f32_e32 v92, v92, v110
	v_sub_f32_e32 v93, v93, v110
	v_sub_f32_e32 v94, v94, v110
	v_sub_f32_e32 v95, v95, v110
	v_sub_f32_e32 v96, v96, v111
	v_sub_f32_e32 v97, v97, v111
	v_sub_f32_e32 v98, v98, v111
	v_sub_f32_e32 v99, v99, v111
	v_sub_f32_e32 v100, v100, v111
	v_sub_f32_e32 v101, v101, v111
	v_sub_f32_e32 v102, v102, v111
	v_sub_f32_e32 v103, v103, v111
	v_mul_f32_e32 v104, v72, v72
	v_fmac_f32_e32 v104, v73, v73
	v_fmac_f32_e32 v104, v74, v74
	v_fmac_f32_e32 v104, v75, v75
	v_fmac_f32_e32 v104, v76, v76
	v_fmac_f32_e32 v104, v77, v77
	v_fmac_f32_e32 v104, v78, v78
	v_fmac_f32_e32 v104, v79, v79
	v_mul_f32_e32 v105, v80, v80
	v_fmac_f32_e32 v105, v81, v81
	v_fmac_f32_e32 v105, v82, v82
	v_fmac_f32_e32 v105, v83, v83
	v_fmac_f32_e32 v105, v84, v84
	v_fmac_f32_e32 v105, v85, v85
	v_fmac_f32_e32 v105, v86, v86
	v_fmac_f32_e32 v105, v87, v87
	v_mul_f32_e32 v106, v88, v88
	v_fmac_f32_e32 v106, v89, v89
	v_fmac_f32_e32 v106, v90, v90
	v_fmac_f32_e32 v106, v91, v91
	v_fmac_f32_e32 v106, v92, v92
	v_fmac_f32_e32 v106, v93, v93
	v_fmac_f32_e32 v106, v94, v94
	v_fmac_f32_e32 v106, v95, v95
	v_mul_f32_e32 v107, v96, v96
	v_fmac_f32_e32 v107, v97, v97
	v_fmac_f32_e32 v107, v98, v98
	v_fmac_f32_e32 v107, v99, v99
	v_fmac_f32_e32 v107, v100, v100
	v_fmac_f32_e32 v107, v101, v101
	v_fmac_f32_e32 v107, v102, v102
	v_fmac_f32_e32 v107, v103, v103
	v_add_f32_dpp v104, v104, v104 quad_perm:[1,0,3,2] row_mask:0xf bank_mask:0xf
	v_add_f32_dpp v105, v105, v105 quad_perm:[1,0,3,2] row_mask:0xf bank_mask:0xf
	v_add_f32_dpp v106, v106, v106 quad_perm:[1,0,3,2] row_mask:0xf bank_mask:0xf
	v_add_f32_dpp v107, v107, v107 quad_perm:[1,0,3,2] row_mask:0xf bank_mask:0xf
	v_add_f32_dpp v104, v104, v104 quad_perm:[2,3,0,1] row_mask:0xf bank_mask:0xf
	v_add_f32_dpp v105, v105, v105 quad_perm:[2,3,0,1] row_mask:0xf bank_mask:0xf
	v_add_f32_dpp v106, v106, v106 quad_perm:[2,3,0,1] row_mask:0xf bank_mask:0xf
	v_add_f32_dpp v107, v107, v107 quad_perm:[2,3,0,1] row_mask:0xf bank_mask:0xf
	v_add_f32_dpp v104, v104, v104 row_half_mirror row_mask:0xf bank_mask:0xf
	v_add_f32_dpp v105, v105, v105 row_half_mirror row_mask:0xf bank_mask:0xf
	v_add_f32_dpp v106, v106, v106 row_half_mirror row_mask:0xf bank_mask:0xf
	v_add_f32_dpp v107, v107, v107 row_half_mirror row_mask:0xf bank_mask:0xf
	v_add_f32_dpp v104, v104, v104 row_mirror row_mask:0xf bank_mask:0xf
	v_add_f32_dpp v105, v105, v105 row_mirror row_mask:0xf bank_mask:0xf
	v_add_f32_dpp v106, v106, v106 row_mirror row_mask:0xf bank_mask:0xf
	v_add_f32_dpp v107, v107, v107 row_mirror row_mask:0xf bank_mask:0xf
	v_add_f32_dpp v104, v104, v104 row_bcast:15 row_mask:0xa bank_mask:0xf
	v_add_f32_dpp v105, v105, v105 row_bcast:15 row_mask:0xa bank_mask:0xf
	v_add_f32_dpp v106, v106, v106 row_bcast:15 row_mask:0xa bank_mask:0xf
	v_add_f32_dpp v107, v107, v107 row_bcast:15 row_mask:0xa bank_mask:0xf
	v_add_f32_dpp v104, v104, v104 row_bcast:31 row_mask:0xc bank_mask:0xf
	v_add_f32_dpp v105, v105, v105 row_bcast:31 row_mask:0xc bank_mask:0xf
	v_add_f32_dpp v106, v106, v106 row_bcast:31 row_mask:0xc bank_mask:0xf
	v_add_f32_dpp v107, v107, v107 row_bcast:31 row_mask:0xc bank_mask:0xf
	v_readlane_b32 s24, v104, 63
	v_readlane_b32 s25, v105, 63
	v_readlane_b32 s26, v106, 63
	v_readlane_b32 s27, v107, 63
	s_nop 0
	v_fma_f32 v108, s24, v7, v132
	v_fma_f32 v109, s25, v7, v132
	v_fma_f32 v110, s26, v7, v132
	v_fma_f32 v111, s27, v7, v132
	v_rsq_f32_e32 v108, v108
	v_rsq_f32_e32 v109, v109
	v_rsq_f32_e32 v110, v110
	v_rsq_f32_e32 v111, v111
	s_nop 0
	v_mul_f32_e32 v72, v72, v108
	v_mul_f32_e32 v73, v73, v108
	v_mul_f32_e32 v74, v74, v108
	v_mul_f32_e32 v75, v75, v108
	v_mul_f32_e32 v76, v76, v108
	v_mul_f32_e32 v77, v77, v108
	v_mul_f32_e32 v78, v78, v108
	v_mul_f32_e32 v79, v79, v108
	v_fma_f32 v72, v72, v112, v120
	v_fma_f32 v73, v73, v113, v121
	v_fma_f32 v74, v74, v114, v122
	v_fma_f32 v75, v75, v115, v123
	v_fma_f32 v76, v76, v116, v124
	v_fma_f32 v77, v77, v117, v125
	v_fma_f32 v78, v78, v118, v126
	v_fma_f32 v79, v79, v119, v127
	v_mul_f32_e32 v80, v80, v109
	v_mul_f32_e32 v81, v81, v109
	v_mul_f32_e32 v82, v82, v109
	v_mul_f32_e32 v83, v83, v109
	v_mul_f32_e32 v84, v84, v109
	v_mul_f32_e32 v85, v85, v109
	v_mul_f32_e32 v86, v86, v109
	v_mul_f32_e32 v87, v87, v109
	v_fma_f32 v80, v80, v112, v120
	v_fma_f32 v81, v81, v113, v121
	v_fma_f32 v82, v82, v114, v122
	v_fma_f32 v83, v83, v115, v123
	v_fma_f32 v84, v84, v116, v124
	v_fma_f32 v85, v85, v117, v125
	v_fma_f32 v86, v86, v118, v126
	v_fma_f32 v87, v87, v119, v127
	v_mul_f32_e32 v88, v88, v110
	v_mul_f32_e32 v89, v89, v110
	v_mul_f32_e32 v90, v90, v110
	v_mul_f32_e32 v91, v91, v110
	v_mul_f32_e32 v92, v92, v110
	v_mul_f32_e32 v93, v93, v110
	v_mul_f32_e32 v94, v94, v110
	v_mul_f32_e32 v95, v95, v110
	v_fma_f32 v88, v88, v112, v120
	v_fma_f32 v89, v89, v113, v121
	v_fma_f32 v90, v90, v114, v122
	v_fma_f32 v91, v91, v115, v123
	v_fma_f32 v92, v92, v116, v124
	v_fma_f32 v93, v93, v117, v125
	v_fma_f32 v94, v94, v118, v126
	v_fma_f32 v95, v95, v119, v127
	v_mul_f32_e32 v96, v96, v111
	v_mul_f32_e32 v97, v97, v111
	v_mul_f32_e32 v98, v98, v111
	v_mul_f32_e32 v99, v99, v111
	v_mul_f32_e32 v100, v100, v111
	v_mul_f32_e32 v101, v101, v111
	v_mul_f32_e32 v102, v102, v111
	v_mul_f32_e32 v103, v103, v111
	v_fma_f32 v96, v96, v112, v120
	v_fma_f32 v97, v97, v113, v121
	v_fma_f32 v98, v98, v114, v122
	v_fma_f32 v99, v99, v115, v123
	v_fma_f32 v100, v100, v116, v124
	v_fma_f32 v101, v101, v117, v125
	v_fma_f32 v102, v102, v118, v126
	v_fma_f32 v103, v103, v119, v127
	v_cvt_pk_bf16_f32 v24, v72, v73
	v_cvt_pk_bf16_f32 v25, v74, v75
	v_cvt_pk_bf16_f32 v26, v76, v77
	v_cvt_pk_bf16_f32 v27, v78, v79
	v_cvt_pk_bf16_f32 v28, v80, v81
	v_cvt_pk_bf16_f32 v29, v82, v83
	v_cvt_pk_bf16_f32 v30, v84, v85
	v_cvt_pk_bf16_f32 v31, v86, v87
	v_cvt_pk_bf16_f32 v32, v88, v89
	v_cvt_pk_bf16_f32 v33, v90, v91
	v_cvt_pk_bf16_f32 v34, v92, v93
	v_cvt_pk_bf16_f32 v35, v94, v95
	v_cvt_pk_bf16_f32 v36, v96, v97
	v_cvt_pk_bf16_f32 v37, v98, v99
	v_cvt_pk_bf16_f32 v38, v100, v101
	v_cvt_pk_bf16_f32 v39, v102, v103
	ds_write_b128 v128, v[24:27] offset:4096
	ds_write_b128 v129, v[28:31] offset:5120
	ds_write_b128 v130, v[32:35] offset:6144
	ds_write_b128 v131, v[36:39] offset:7168
	s_waitcnt vmcnt(20)
	v_lshlrev_b32_e32 v72, 16, v40
	v_and_b32_e32 v73, 0xffff0000, v40
	v_lshlrev_b32_e32 v74, 16, v41
	v_and_b32_e32 v75, 0xffff0000, v41
	v_lshlrev_b32_e32 v76, 16, v42
	v_and_b32_e32 v77, 0xffff0000, v42
	v_lshlrev_b32_e32 v78, 16, v43
	v_and_b32_e32 v79, 0xffff0000, v43
	v_lshlrev_b32_e32 v80, 16, v44
	v_and_b32_e32 v81, 0xffff0000, v44
	v_lshlrev_b32_e32 v82, 16, v45
	v_and_b32_e32 v83, 0xffff0000, v45
	v_lshlrev_b32_e32 v84, 16, v46
	v_and_b32_e32 v85, 0xffff0000, v46
	v_lshlrev_b32_e32 v86, 16, v47
	v_and_b32_e32 v87, 0xffff0000, v47
	v_lshlrev_b32_e32 v88, 16, v48
	v_and_b32_e32 v89, 0xffff0000, v48
	v_lshlrev_b32_e32 v90, 16, v49
	v_and_b32_e32 v91, 0xffff0000, v49
	v_lshlrev_b32_e32 v92, 16, v50
	v_and_b32_e32 v93, 0xffff0000, v50
	v_lshlrev_b32_e32 v94, 16, v51
	v_and_b32_e32 v95, 0xffff0000, v51
	v_lshlrev_b32_e32 v96, 16, v52
	v_and_b32_e32 v97, 0xffff0000, v52
	v_lshlrev_b32_e32 v98, 16, v53
	v_and_b32_e32 v99, 0xffff0000, v53
	v_lshlrev_b32_e32 v100, 16, v54
	v_and_b32_e32 v101, 0xffff0000, v54
	v_lshlrev_b32_e32 v102, 16, v55
	v_and_b32_e32 v103, 0xffff0000, v55
	v_add_f32_e32 v104, v72, v73
	v_add_f32_e32 v104, v104, v74
	v_add_f32_e32 v104, v104, v75
	v_add_f32_e32 v104, v104, v76
	v_add_f32_e32 v104, v104, v77
	v_add_f32_e32 v104, v104, v78
	v_add_f32_e32 v104, v104, v79
	v_add_f32_e32 v105, v80, v81
	v_add_f32_e32 v105, v105, v82
	v_add_f32_e32 v105, v105, v83
	v_add_f32_e32 v105, v105, v84
	v_add_f32_e32 v105, v105, v85
	v_add_f32_e32 v105, v105, v86
	v_add_f32_e32 v105, v105, v87
	v_add_f32_e32 v106, v88, v89
	v_add_f32_e32 v106, v106, v90
	v_add_f32_e32 v106, v106, v91
	v_add_f32_e32 v106, v106, v92
	v_add_f32_e32 v106, v106, v93
	v_add_f32_e32 v106, v106, v94
	v_add_f32_e32 v106, v106, v95
	v_add_f32_e32 v107, v96, v97
	v_add_f32_e32 v107, v107, v98
	v_add_f32_e32 v107, v107, v99
	v_add_f32_e32 v107, v107, v100
	v_add_f32_e32 v107, v107, v101
	v_add_f32_e32 v107, v107, v102
	v_add_f32_e32 v107, v107, v103
	v_add_f32_dpp v104, v104, v104 quad_perm:[1,0,3,2] row_mask:0xf bank_mask:0xf
	v_add_f32_dpp v105, v105, v105 quad_perm:[1,0,3,2] row_mask:0xf bank_mask:0xf
	v_add_f32_dpp v106, v106, v106 quad_perm:[1,0,3,2] row_mask:0xf bank_mask:0xf
	v_add_f32_dpp v107, v107, v107 quad_perm:[1,0,3,2] row_mask:0xf bank_mask:0xf
	v_add_f32_dpp v104, v104, v104 quad_perm:[2,3,0,1] row_mask:0xf bank_mask:0xf
	v_add_f32_dpp v105, v105, v105 quad_perm:[2,3,0,1] row_mask:0xf bank_mask:0xf
	v_add_f32_dpp v106, v106, v106 quad_perm:[2,3,0,1] row_mask:0xf bank_mask:0xf
	v_add_f32_dpp v107, v107, v107 quad_perm:[2,3,0,1] row_mask:0xf bank_mask:0xf
	v_add_f32_dpp v104, v104, v104 row_half_mirror row_mask:0xf bank_mask:0xf
	v_add_f32_dpp v105, v105, v105 row_half_mirror row_mask:0xf bank_mask:0xf
	v_add_f32_dpp v106, v106, v106 row_half_mirror row_mask:0xf bank_mask:0xf
	v_add_f32_dpp v107, v107, v107 row_half_mirror row_mask:0xf bank_mask:0xf
	v_add_f32_dpp v104, v104, v104 row_mirror row_mask:0xf bank_mask:0xf
	v_add_f32_dpp v105, v105, v105 row_mirror row_mask:0xf bank_mask:0xf
	v_add_f32_dpp v106, v106, v106 row_mirror row_mask:0xf bank_mask:0xf
	v_add_f32_dpp v107, v107, v107 row_mirror row_mask:0xf bank_mask:0xf
	v_add_f32_dpp v104, v104, v104 row_bcast:15 row_mask:0xa bank_mask:0xf
	v_add_f32_dpp v105, v105, v105 row_bcast:15 row_mask:0xa bank_mask:0xf
	v_add_f32_dpp v106, v106, v106 row_bcast:15 row_mask:0xa bank_mask:0xf
	v_add_f32_dpp v107, v107, v107 row_bcast:15 row_mask:0xa bank_mask:0xf
	v_add_f32_dpp v104, v104, v104 row_bcast:31 row_mask:0xc bank_mask:0xf
	v_add_f32_dpp v105, v105, v105 row_bcast:31 row_mask:0xc bank_mask:0xf
	v_add_f32_dpp v106, v106, v106 row_bcast:31 row_mask:0xc bank_mask:0xf
	v_add_f32_dpp v107, v107, v107 row_bcast:31 row_mask:0xc bank_mask:0xf
	v_readlane_b32 s24, v104, 63
	v_readlane_b32 s25, v105, 63
	v_readlane_b32 s26, v106, 63
	v_readlane_b32 s27, v107, 63
	s_nop 0
	v_mul_f32_e32 v108, s24, v7
	v_mul_f32_e32 v109, s25, v7
	v_mul_f32_e32 v110, s26, v7
	v_mul_f32_e32 v111, s27, v7
	v_sub_f32_e32 v72, v72, v108
	v_sub_f32_e32 v73, v73, v108
	v_sub_f32_e32 v74, v74, v108
	v_sub_f32_e32 v75, v75, v108
	v_sub_f32_e32 v76, v76, v108
	v_sub_f32_e32 v77, v77, v108
	v_sub_f32_e32 v78, v78, v108
	v_sub_f32_e32 v79, v79, v108
	v_sub_f32_e32 v80, v80, v109
	v_sub_f32_e32 v81, v81, v109
	v_sub_f32_e32 v82, v82, v109
	v_sub_f32_e32 v83, v83, v109
	v_sub_f32_e32 v84, v84, v109
	v_sub_f32_e32 v85, v85, v109
	v_sub_f32_e32 v86, v86, v109
	v_sub_f32_e32 v87, v87, v109
	v_sub_f32_e32 v88, v88, v110
	v_sub_f32_e32 v89, v89, v110
	v_sub_f32_e32 v90, v90, v110
	v_sub_f32_e32 v91, v91, v110
	v_sub_f32_e32 v92, v92, v110
	v_sub_f32_e32 v93, v93, v110
	v_sub_f32_e32 v94, v94, v110
	v_sub_f32_e32 v95, v95, v110
	v_sub_f32_e32 v96, v96, v111
	v_sub_f32_e32 v97, v97, v111
	v_sub_f32_e32 v98, v98, v111
	v_sub_f32_e32 v99, v99, v111
	v_sub_f32_e32 v100, v100, v111
	v_sub_f32_e32 v101, v101, v111
	v_sub_f32_e32 v102, v102, v111
	v_sub_f32_e32 v103, v103, v111
	v_mul_f32_e32 v104, v72, v72
	v_fmac_f32_e32 v104, v73, v73
	v_fmac_f32_e32 v104, v74, v74
	v_fmac_f32_e32 v104, v75, v75
	v_fmac_f32_e32 v104, v76, v76
	v_fmac_f32_e32 v104, v77, v77
	v_fmac_f32_e32 v104, v78, v78
	v_fmac_f32_e32 v104, v79, v79
	v_mul_f32_e32 v105, v80, v80
	v_fmac_f32_e32 v105, v81, v81
	v_fmac_f32_e32 v105, v82, v82
	v_fmac_f32_e32 v105, v83, v83
	v_fmac_f32_e32 v105, v84, v84
	v_fmac_f32_e32 v105, v85, v85
	v_fmac_f32_e32 v105, v86, v86
	v_fmac_f32_e32 v105, v87, v87
	v_mul_f32_e32 v106, v88, v88
	v_fmac_f32_e32 v106, v89, v89
	v_fmac_f32_e32 v106, v90, v90
	v_fmac_f32_e32 v106, v91, v91
	v_fmac_f32_e32 v106, v92, v92
	v_fmac_f32_e32 v106, v93, v93
	v_fmac_f32_e32 v106, v94, v94
	v_fmac_f32_e32 v106, v95, v95
	v_mul_f32_e32 v107, v96, v96
	v_fmac_f32_e32 v107, v97, v97
	v_fmac_f32_e32 v107, v98, v98
	v_fmac_f32_e32 v107, v99, v99
	v_fmac_f32_e32 v107, v100, v100
	v_fmac_f32_e32 v107, v101, v101
	v_fmac_f32_e32 v107, v102, v102
	v_fmac_f32_e32 v107, v103, v103
	v_add_f32_dpp v104, v104, v104 quad_perm:[1,0,3,2] row_mask:0xf bank_mask:0xf
	v_add_f32_dpp v105, v105, v105 quad_perm:[1,0,3,2] row_mask:0xf bank_mask:0xf
	v_add_f32_dpp v106, v106, v106 quad_perm:[1,0,3,2] row_mask:0xf bank_mask:0xf
	v_add_f32_dpp v107, v107, v107 quad_perm:[1,0,3,2] row_mask:0xf bank_mask:0xf
	v_add_f32_dpp v104, v104, v104 quad_perm:[2,3,0,1] row_mask:0xf bank_mask:0xf
	v_add_f32_dpp v105, v105, v105 quad_perm:[2,3,0,1] row_mask:0xf bank_mask:0xf
	v_add_f32_dpp v106, v106, v106 quad_perm:[2,3,0,1] row_mask:0xf bank_mask:0xf
	v_add_f32_dpp v107, v107, v107 quad_perm:[2,3,0,1] row_mask:0xf bank_mask:0xf
	v_add_f32_dpp v104, v104, v104 row_half_mirror row_mask:0xf bank_mask:0xf
	v_add_f32_dpp v105, v105, v105 row_half_mirror row_mask:0xf bank_mask:0xf
	v_add_f32_dpp v106, v106, v106 row_half_mirror row_mask:0xf bank_mask:0xf
	v_add_f32_dpp v107, v107, v107 row_half_mirror row_mask:0xf bank_mask:0xf
	v_add_f32_dpp v104, v104, v104 row_mirror row_mask:0xf bank_mask:0xf
	v_add_f32_dpp v105, v105, v105 row_mirror row_mask:0xf bank_mask:0xf
	v_add_f32_dpp v106, v106, v106 row_mirror row_mask:0xf bank_mask:0xf
	v_add_f32_dpp v107, v107, v107 row_mirror row_mask:0xf bank_mask:0xf
	v_add_f32_dpp v104, v104, v104 row_bcast:15 row_mask:0xa bank_mask:0xf
	v_add_f32_dpp v105, v105, v105 row_bcast:15 row_mask:0xa bank_mask:0xf
	v_add_f32_dpp v106, v106, v106 row_bcast:15 row_mask:0xa bank_mask:0xf
	v_add_f32_dpp v107, v107, v107 row_bcast:15 row_mask:0xa bank_mask:0xf
	v_add_f32_dpp v104, v104, v104 row_bcast:31 row_mask:0xc bank_mask:0xf
	v_add_f32_dpp v105, v105, v105 row_bcast:31 row_mask:0xc bank_mask:0xf
	v_add_f32_dpp v106, v106, v106 row_bcast:31 row_mask:0xc bank_mask:0xf
	v_add_f32_dpp v107, v107, v107 row_bcast:31 row_mask:0xc bank_mask:0xf
	v_readlane_b32 s24, v104, 63
	v_readlane_b32 s25, v105, 63
	v_readlane_b32 s26, v106, 63
	v_readlane_b32 s27, v107, 63
	s_nop 0
	v_fma_f32 v108, s24, v7, v132
	v_fma_f32 v109, s25, v7, v132
	v_fma_f32 v110, s26, v7, v132
	v_fma_f32 v111, s27, v7, v132
	v_rsq_f32_e32 v108, v108
	v_rsq_f32_e32 v109, v109
	v_rsq_f32_e32 v110, v110
	v_rsq_f32_e32 v111, v111
	s_nop 0
	v_mul_f32_e32 v72, v72, v108
	v_mul_f32_e32 v73, v73, v108
	v_mul_f32_e32 v74, v74, v108
	v_mul_f32_e32 v75, v75, v108
	v_mul_f32_e32 v76, v76, v108
	v_mul_f32_e32 v77, v77, v108
	v_mul_f32_e32 v78, v78, v108
	v_mul_f32_e32 v79, v79, v108
	v_fma_f32 v72, v72, v112, v120
	v_fma_f32 v73, v73, v113, v121
	v_fma_f32 v74, v74, v114, v122
	v_fma_f32 v75, v75, v115, v123
	v_fma_f32 v76, v76, v116, v124
	v_fma_f32 v77, v77, v117, v125
	v_fma_f32 v78, v78, v118, v126
	v_fma_f32 v79, v79, v119, v127
	v_mul_f32_e32 v80, v80, v109
	v_mul_f32_e32 v81, v81, v109
	v_mul_f32_e32 v82, v82, v109
	v_mul_f32_e32 v83, v83, v109
	v_mul_f32_e32 v84, v84, v109
	v_mul_f32_e32 v85, v85, v109
	v_mul_f32_e32 v86, v86, v109
	v_mul_f32_e32 v87, v87, v109
	v_fma_f32 v80, v80, v112, v120
	v_fma_f32 v81, v81, v113, v121
	v_fma_f32 v82, v82, v114, v122
	v_fma_f32 v83, v83, v115, v123
	v_fma_f32 v84, v84, v116, v124
	v_fma_f32 v85, v85, v117, v125
	v_fma_f32 v86, v86, v118, v126
	v_fma_f32 v87, v87, v119, v127
	v_mul_f32_e32 v88, v88, v110
	v_mul_f32_e32 v89, v89, v110
	v_mul_f32_e32 v90, v90, v110
	v_mul_f32_e32 v91, v91, v110
	v_mul_f32_e32 v92, v92, v110
	v_mul_f32_e32 v93, v93, v110
	v_mul_f32_e32 v94, v94, v110
	v_mul_f32_e32 v95, v95, v110
	v_fma_f32 v88, v88, v112, v120
	v_fma_f32 v89, v89, v113, v121
	v_fma_f32 v90, v90, v114, v122
	v_fma_f32 v91, v91, v115, v123
	v_fma_f32 v92, v92, v116, v124
	v_fma_f32 v93, v93, v117, v125
	v_fma_f32 v94, v94, v118, v126
	v_fma_f32 v95, v95, v119, v127
	v_mul_f32_e32 v96, v96, v111
	v_mul_f32_e32 v97, v97, v111
	v_mul_f32_e32 v98, v98, v111
	v_mul_f32_e32 v99, v99, v111
	v_mul_f32_e32 v100, v100, v111
	v_mul_f32_e32 v101, v101, v111
	v_mul_f32_e32 v102, v102, v111
	v_mul_f32_e32 v103, v103, v111
	v_fma_f32 v96, v96, v112, v120
	v_fma_f32 v97, v97, v113, v121
	v_fma_f32 v98, v98, v114, v122
	v_fma_f32 v99, v99, v115, v123
	v_fma_f32 v100, v100, v116, v124
	v_fma_f32 v101, v101, v117, v125
	v_fma_f32 v102, v102, v118, v126
	v_fma_f32 v103, v103, v119, v127
	v_cvt_pk_bf16_f32 v40, v72, v73
	v_cvt_pk_bf16_f32 v41, v74, v75
	v_cvt_pk_bf16_f32 v42, v76, v77
	v_cvt_pk_bf16_f32 v43, v78, v79
	v_cvt_pk_bf16_f32 v44, v80, v81
	v_cvt_pk_bf16_f32 v45, v82, v83
	v_cvt_pk_bf16_f32 v46, v84, v85
	v_cvt_pk_bf16_f32 v47, v86, v87
	v_cvt_pk_bf16_f32 v48, v88, v89
	v_cvt_pk_bf16_f32 v49, v90, v91
	v_cvt_pk_bf16_f32 v50, v92, v93
	v_cvt_pk_bf16_f32 v51, v94, v95
	v_cvt_pk_bf16_f32 v52, v96, v97
	v_cvt_pk_bf16_f32 v53, v98, v99
	v_cvt_pk_bf16_f32 v54, v100, v101
	v_cvt_pk_bf16_f32 v55, v102, v103
	ds_write_b128 v128, v[40:43] offset:8192
	ds_write_b128 v129, v[44:47] offset:9216
	ds_write_b128 v130, v[48:51] offset:10240
	ds_write_b128 v131, v[52:55] offset:11264
	s_waitcnt vmcnt(16)
	v_lshlrev_b32_e32 v72, 16, v56
	v_and_b32_e32 v73, 0xffff0000, v56
	v_lshlrev_b32_e32 v74, 16, v57
	v_and_b32_e32 v75, 0xffff0000, v57
	v_lshlrev_b32_e32 v76, 16, v58
	v_and_b32_e32 v77, 0xffff0000, v58
	v_lshlrev_b32_e32 v78, 16, v59
	v_and_b32_e32 v79, 0xffff0000, v59
	v_lshlrev_b32_e32 v80, 16, v60
	v_and_b32_e32 v81, 0xffff0000, v60
	v_lshlrev_b32_e32 v82, 16, v61
	v_and_b32_e32 v83, 0xffff0000, v61
	v_lshlrev_b32_e32 v84, 16, v62
	v_and_b32_e32 v85, 0xffff0000, v62
	v_lshlrev_b32_e32 v86, 16, v63
	v_and_b32_e32 v87, 0xffff0000, v63
	v_lshlrev_b32_e32 v88, 16, v64
	v_and_b32_e32 v89, 0xffff0000, v64
	v_lshlrev_b32_e32 v90, 16, v65
	v_and_b32_e32 v91, 0xffff0000, v65
	v_lshlrev_b32_e32 v92, 16, v66
	v_and_b32_e32 v93, 0xffff0000, v66
	v_lshlrev_b32_e32 v94, 16, v67
	v_and_b32_e32 v95, 0xffff0000, v67
	v_lshlrev_b32_e32 v96, 16, v68
	v_and_b32_e32 v97, 0xffff0000, v68
	v_lshlrev_b32_e32 v98, 16, v69
	v_and_b32_e32 v99, 0xffff0000, v69
	v_lshlrev_b32_e32 v100, 16, v70
	v_and_b32_e32 v101, 0xffff0000, v70
	v_lshlrev_b32_e32 v102, 16, v71
	v_and_b32_e32 v103, 0xffff0000, v71
	v_add_f32_e32 v104, v72, v73
	v_add_f32_e32 v104, v104, v74
	v_add_f32_e32 v104, v104, v75
	v_add_f32_e32 v104, v104, v76
	v_add_f32_e32 v104, v104, v77
	v_add_f32_e32 v104, v104, v78
	v_add_f32_e32 v104, v104, v79
	v_add_f32_e32 v105, v80, v81
	v_add_f32_e32 v105, v105, v82
	v_add_f32_e32 v105, v105, v83
	v_add_f32_e32 v105, v105, v84
	v_add_f32_e32 v105, v105, v85
	v_add_f32_e32 v105, v105, v86
	v_add_f32_e32 v105, v105, v87
	v_add_f32_e32 v106, v88, v89
	v_add_f32_e32 v106, v106, v90
	v_add_f32_e32 v106, v106, v91
	v_add_f32_e32 v106, v106, v92
	v_add_f32_e32 v106, v106, v93
	v_add_f32_e32 v106, v106, v94
	v_add_f32_e32 v106, v106, v95
	v_add_f32_e32 v107, v96, v97
	v_add_f32_e32 v107, v107, v98
	v_add_f32_e32 v107, v107, v99
	v_add_f32_e32 v107, v107, v100
	v_add_f32_e32 v107, v107, v101
	v_add_f32_e32 v107, v107, v102
	v_add_f32_e32 v107, v107, v103
	v_add_f32_dpp v104, v104, v104 quad_perm:[1,0,3,2] row_mask:0xf bank_mask:0xf
	v_add_f32_dpp v105, v105, v105 quad_perm:[1,0,3,2] row_mask:0xf bank_mask:0xf
	v_add_f32_dpp v106, v106, v106 quad_perm:[1,0,3,2] row_mask:0xf bank_mask:0xf
	v_add_f32_dpp v107, v107, v107 quad_perm:[1,0,3,2] row_mask:0xf bank_mask:0xf
	v_add_f32_dpp v104, v104, v104 quad_perm:[2,3,0,1] row_mask:0xf bank_mask:0xf
	v_add_f32_dpp v105, v105, v105 quad_perm:[2,3,0,1] row_mask:0xf bank_mask:0xf
	v_add_f32_dpp v106, v106, v106 quad_perm:[2,3,0,1] row_mask:0xf bank_mask:0xf
	v_add_f32_dpp v107, v107, v107 quad_perm:[2,3,0,1] row_mask:0xf bank_mask:0xf
	v_add_f32_dpp v104, v104, v104 row_half_mirror row_mask:0xf bank_mask:0xf
	v_add_f32_dpp v105, v105, v105 row_half_mirror row_mask:0xf bank_mask:0xf
	v_add_f32_dpp v106, v106, v106 row_half_mirror row_mask:0xf bank_mask:0xf
	v_add_f32_dpp v107, v107, v107 row_half_mirror row_mask:0xf bank_mask:0xf
	v_add_f32_dpp v104, v104, v104 row_mirror row_mask:0xf bank_mask:0xf
	v_add_f32_dpp v105, v105, v105 row_mirror row_mask:0xf bank_mask:0xf
	v_add_f32_dpp v106, v106, v106 row_mirror row_mask:0xf bank_mask:0xf
	v_add_f32_dpp v107, v107, v107 row_mirror row_mask:0xf bank_mask:0xf
	v_add_f32_dpp v104, v104, v104 row_bcast:15 row_mask:0xa bank_mask:0xf
	v_add_f32_dpp v105, v105, v105 row_bcast:15 row_mask:0xa bank_mask:0xf
	v_add_f32_dpp v106, v106, v106 row_bcast:15 row_mask:0xa bank_mask:0xf
	v_add_f32_dpp v107, v107, v107 row_bcast:15 row_mask:0xa bank_mask:0xf
	v_add_f32_dpp v104, v104, v104 row_bcast:31 row_mask:0xc bank_mask:0xf
	v_add_f32_dpp v105, v105, v105 row_bcast:31 row_mask:0xc bank_mask:0xf
	v_add_f32_dpp v106, v106, v106 row_bcast:31 row_mask:0xc bank_mask:0xf
	v_add_f32_dpp v107, v107, v107 row_bcast:31 row_mask:0xc bank_mask:0xf
	v_readlane_b32 s24, v104, 63
	v_readlane_b32 s25, v105, 63
	v_readlane_b32 s26, v106, 63
	v_readlane_b32 s27, v107, 63
	s_nop 0
	v_mul_f32_e32 v108, s24, v7
	v_mul_f32_e32 v109, s25, v7
	v_mul_f32_e32 v110, s26, v7
	v_mul_f32_e32 v111, s27, v7
	v_sub_f32_e32 v72, v72, v108
	v_sub_f32_e32 v73, v73, v108
	v_sub_f32_e32 v74, v74, v108
	v_sub_f32_e32 v75, v75, v108
	v_sub_f32_e32 v76, v76, v108
	v_sub_f32_e32 v77, v77, v108
	v_sub_f32_e32 v78, v78, v108
	v_sub_f32_e32 v79, v79, v108
	v_sub_f32_e32 v80, v80, v109
	v_sub_f32_e32 v81, v81, v109
	v_sub_f32_e32 v82, v82, v109
	v_sub_f32_e32 v83, v83, v109
	v_sub_f32_e32 v84, v84, v109
	v_sub_f32_e32 v85, v85, v109
	v_sub_f32_e32 v86, v86, v109
	v_sub_f32_e32 v87, v87, v109
	v_sub_f32_e32 v88, v88, v110
	v_sub_f32_e32 v89, v89, v110
	v_sub_f32_e32 v90, v90, v110
	v_sub_f32_e32 v91, v91, v110
	v_sub_f32_e32 v92, v92, v110
	v_sub_f32_e32 v93, v93, v110
	v_sub_f32_e32 v94, v94, v110
	v_sub_f32_e32 v95, v95, v110
	v_sub_f32_e32 v96, v96, v111
	v_sub_f32_e32 v97, v97, v111
	v_sub_f32_e32 v98, v98, v111
	v_sub_f32_e32 v99, v99, v111
	v_sub_f32_e32 v100, v100, v111
	v_sub_f32_e32 v101, v101, v111
	v_sub_f32_e32 v102, v102, v111
	v_sub_f32_e32 v103, v103, v111
	v_mul_f32_e32 v104, v72, v72
	v_fmac_f32_e32 v104, v73, v73
	v_fmac_f32_e32 v104, v74, v74
	v_fmac_f32_e32 v104, v75, v75
	v_fmac_f32_e32 v104, v76, v76
	v_fmac_f32_e32 v104, v77, v77
	v_fmac_f32_e32 v104, v78, v78
	v_fmac_f32_e32 v104, v79, v79
	v_mul_f32_e32 v105, v80, v80
	v_fmac_f32_e32 v105, v81, v81
	v_fmac_f32_e32 v105, v82, v82
	v_fmac_f32_e32 v105, v83, v83
	v_fmac_f32_e32 v105, v84, v84
	v_fmac_f32_e32 v105, v85, v85
	v_fmac_f32_e32 v105, v86, v86
	v_fmac_f32_e32 v105, v87, v87
	v_mul_f32_e32 v106, v88, v88
	v_fmac_f32_e32 v106, v89, v89
	v_fmac_f32_e32 v106, v90, v90
	v_fmac_f32_e32 v106, v91, v91
	v_fmac_f32_e32 v106, v92, v92
	v_fmac_f32_e32 v106, v93, v93
	v_fmac_f32_e32 v106, v94, v94
	v_fmac_f32_e32 v106, v95, v95
	v_mul_f32_e32 v107, v96, v96
	v_fmac_f32_e32 v107, v97, v97
	v_fmac_f32_e32 v107, v98, v98
	v_fmac_f32_e32 v107, v99, v99
	v_fmac_f32_e32 v107, v100, v100
	v_fmac_f32_e32 v107, v101, v101
	v_fmac_f32_e32 v107, v102, v102
	v_fmac_f32_e32 v107, v103, v103
	v_add_f32_dpp v104, v104, v104 quad_perm:[1,0,3,2] row_mask:0xf bank_mask:0xf
	v_add_f32_dpp v105, v105, v105 quad_perm:[1,0,3,2] row_mask:0xf bank_mask:0xf
	v_add_f32_dpp v106, v106, v106 quad_perm:[1,0,3,2] row_mask:0xf bank_mask:0xf
	v_add_f32_dpp v107, v107, v107 quad_perm:[1,0,3,2] row_mask:0xf bank_mask:0xf
	v_add_f32_dpp v104, v104, v104 quad_perm:[2,3,0,1] row_mask:0xf bank_mask:0xf
	v_add_f32_dpp v105, v105, v105 quad_perm:[2,3,0,1] row_mask:0xf bank_mask:0xf
	v_add_f32_dpp v106, v106, v106 quad_perm:[2,3,0,1] row_mask:0xf bank_mask:0xf
	v_add_f32_dpp v107, v107, v107 quad_perm:[2,3,0,1] row_mask:0xf bank_mask:0xf
	v_add_f32_dpp v104, v104, v104 row_half_mirror row_mask:0xf bank_mask:0xf
	v_add_f32_dpp v105, v105, v105 row_half_mirror row_mask:0xf bank_mask:0xf
	v_add_f32_dpp v106, v106, v106 row_half_mirror row_mask:0xf bank_mask:0xf
	v_add_f32_dpp v107, v107, v107 row_half_mirror row_mask:0xf bank_mask:0xf
	v_add_f32_dpp v104, v104, v104 row_mirror row_mask:0xf bank_mask:0xf
	v_add_f32_dpp v105, v105, v105 row_mirror row_mask:0xf bank_mask:0xf
	v_add_f32_dpp v106, v106, v106 row_mirror row_mask:0xf bank_mask:0xf
	v_add_f32_dpp v107, v107, v107 row_mirror row_mask:0xf bank_mask:0xf
	v_add_f32_dpp v104, v104, v104 row_bcast:15 row_mask:0xa bank_mask:0xf
	v_add_f32_dpp v105, v105, v105 row_bcast:15 row_mask:0xa bank_mask:0xf
	v_add_f32_dpp v106, v106, v106 row_bcast:15 row_mask:0xa bank_mask:0xf
	v_add_f32_dpp v107, v107, v107 row_bcast:15 row_mask:0xa bank_mask:0xf
	v_add_f32_dpp v104, v104, v104 row_bcast:31 row_mask:0xc bank_mask:0xf
	v_add_f32_dpp v105, v105, v105 row_bcast:31 row_mask:0xc bank_mask:0xf
	v_add_f32_dpp v106, v106, v106 row_bcast:31 row_mask:0xc bank_mask:0xf
	v_add_f32_dpp v107, v107, v107 row_bcast:31 row_mask:0xc bank_mask:0xf
	v_readlane_b32 s24, v104, 63
	v_readlane_b32 s25, v105, 63
	v_readlane_b32 s26, v106, 63
	v_readlane_b32 s27, v107, 63
	s_nop 0
	v_fma_f32 v108, s24, v7, v132
	v_fma_f32 v109, s25, v7, v132
	v_fma_f32 v110, s26, v7, v132
	v_fma_f32 v111, s27, v7, v132
	v_rsq_f32_e32 v108, v108
	v_rsq_f32_e32 v109, v109
	v_rsq_f32_e32 v110, v110
	v_rsq_f32_e32 v111, v111
	s_nop 0
	v_mul_f32_e32 v72, v72, v108
	v_mul_f32_e32 v73, v73, v108
	v_mul_f32_e32 v74, v74, v108
	v_mul_f32_e32 v75, v75, v108
	v_mul_f32_e32 v76, v76, v108
	v_mul_f32_e32 v77, v77, v108
	v_mul_f32_e32 v78, v78, v108
	v_mul_f32_e32 v79, v79, v108
	v_fma_f32 v72, v72, v112, v120
	v_fma_f32 v73, v73, v113, v121
	v_fma_f32 v74, v74, v114, v122
	v_fma_f32 v75, v75, v115, v123
	v_fma_f32 v76, v76, v116, v124
	v_fma_f32 v77, v77, v117, v125
	v_fma_f32 v78, v78, v118, v126
	v_fma_f32 v79, v79, v119, v127
	v_mul_f32_e32 v80, v80, v109
	v_mul_f32_e32 v81, v81, v109
	v_mul_f32_e32 v82, v82, v109
	v_mul_f32_e32 v83, v83, v109
	v_mul_f32_e32 v84, v84, v109
	v_mul_f32_e32 v85, v85, v109
	v_mul_f32_e32 v86, v86, v109
	v_mul_f32_e32 v87, v87, v109
	v_fma_f32 v80, v80, v112, v120
	v_fma_f32 v81, v81, v113, v121
	v_fma_f32 v82, v82, v114, v122
	v_fma_f32 v83, v83, v115, v123
	v_fma_f32 v84, v84, v116, v124
	v_fma_f32 v85, v85, v117, v125
	v_fma_f32 v86, v86, v118, v126
	v_fma_f32 v87, v87, v119, v127
	v_mul_f32_e32 v88, v88, v110
	v_mul_f32_e32 v89, v89, v110
	v_mul_f32_e32 v90, v90, v110
	v_mul_f32_e32 v91, v91, v110
	v_mul_f32_e32 v92, v92, v110
	v_mul_f32_e32 v93, v93, v110
	v_mul_f32_e32 v94, v94, v110
	v_mul_f32_e32 v95, v95, v110
	v_fma_f32 v88, v88, v112, v120
	v_fma_f32 v89, v89, v113, v121
	v_fma_f32 v90, v90, v114, v122
	v_fma_f32 v91, v91, v115, v123
	v_fma_f32 v92, v92, v116, v124
	v_fma_f32 v93, v93, v117, v125
	v_fma_f32 v94, v94, v118, v126
	v_fma_f32 v95, v95, v119, v127
	v_mul_f32_e32 v96, v96, v111
	v_mul_f32_e32 v97, v97, v111
	v_mul_f32_e32 v98, v98, v111
	v_mul_f32_e32 v99, v99, v111
	v_mul_f32_e32 v100, v100, v111
	v_mul_f32_e32 v101, v101, v111
	v_mul_f32_e32 v102, v102, v111
	v_mul_f32_e32 v103, v103, v111
	v_fma_f32 v96, v96, v112, v120
	v_fma_f32 v97, v97, v113, v121
	v_fma_f32 v98, v98, v114, v122
	v_fma_f32 v99, v99, v115, v123
	v_fma_f32 v100, v100, v116, v124
	v_fma_f32 v101, v101, v117, v125
	v_fma_f32 v102, v102, v118, v126
	v_fma_f32 v103, v103, v119, v127
	v_cvt_pk_bf16_f32 v56, v72, v73
	v_cvt_pk_bf16_f32 v57, v74, v75
	v_cvt_pk_bf16_f32 v58, v76, v77
	v_cvt_pk_bf16_f32 v59, v78, v79
	v_cvt_pk_bf16_f32 v60, v80, v81
	v_cvt_pk_bf16_f32 v61, v82, v83
	v_cvt_pk_bf16_f32 v62, v84, v85
	v_cvt_pk_bf16_f32 v63, v86, v87
	v_cvt_pk_bf16_f32 v64, v88, v89
	v_cvt_pk_bf16_f32 v65, v90, v91
	v_cvt_pk_bf16_f32 v66, v92, v93
	v_cvt_pk_bf16_f32 v67, v94, v95
	v_cvt_pk_bf16_f32 v68, v96, v97
	v_cvt_pk_bf16_f32 v69, v98, v99
	v_cvt_pk_bf16_f32 v70, v100, v101
	v_cvt_pk_bf16_f32 v71, v102, v103
	ds_write_b128 v128, v[56:59] offset:12288
	ds_write_b128 v129, v[60:63] offset:13312
	ds_write_b128 v130, v[64:67] offset:14336
	ds_write_b128 v131, v[68:71] offset:15360
	s_waitcnt lgkmcnt(0)
	s_mov_b64 s[34:35], s[32:33]
	s_add_u32 s36, s32, 0x2000
	s_addc_u32 s37, s33, 0
	global_load_dwordx4 v[8:11], v137, s[34:35] offset:0
	global_load_dwordx4 v[12:15], v137, s[34:35] offset:32
	s_add_u32 s34, s34, 0x4000
	s_addc_u32 s35, s35, 0
	global_load_dwordx4 v[16:19], v137, s[36:37] offset:0
	global_load_dwordx4 v[20:23], v137, s[36:37] offset:32
	global_load_dwordx4 v[24:27], v137, s[36:37] offset:64
	global_load_dwordx4 v[28:31], v137, s[36:37] offset:96
	s_add_u32 s36, s36, 0x4000
	s_addc_u32 s37, s37, 0
	global_load_dwordx4 v[32:35], v137, s[34:35] offset:0
	global_load_dwordx4 v[36:39], v137, s[34:35] offset:32
	global_load_dwordx4 v[40:43], v137, s[34:35] offset:64
	global_load_dwordx4 v[44:47], v137, s[34:35] offset:96
	global_load_dwordx4 v[48:51], v137, s[34:35] offset:128
	global_load_dwordx4 v[52:55], v137, s[34:35] offset:160
	global_load_dwordx4 v[56:59], v137, s[36:37] offset:0
	global_load_dwordx4 v[60:63], v137, s[36:37] offset:32
	global_load_dwordx4 v[64:67], v137, s[36:37] offset:64
	global_load_dwordx4 v[68:71], v137, s[36:37] offset:96
	global_load_dwordx4 v[72:75], v137, s[36:37] offset:128
	global_load_dwordx4 v[76:79], v137, s[36:37] offset:160
	global_load_dwordx4 v[80:83], v137, s[36:37] offset:192
	global_load_dwordx4 v[84:87], v137, s[36:37] offset:224
	global_load_dword v88, v140, s[44:45] offset:0
	global_load_dword v89, v140, s[44:45] offset:128
	global_load_dword v90, v140, s[44:45] offset:256
	global_load_dword v91, v140, s[44:45] offset:384
	s_lshl_b32 s4, s1, 18
	s_lshl_b32 s5, s0, 7
	s_add_i32 s5, s5, 0x400
	s_add_u32 s38, s30, s4
	s_addc_u32 s39, s31, 0
	s_add_u32 s38, s38, s5
	s_addc_u32 s39, s39, 0
	s_add_u32 s46, s38, 0x10000
	s_addc_u32 s47, s39, 0
	s_add_u32 s54, s38, 0x20000
	s_addc_u32 s55, s39, 0
	s_add_u32 s56, s38, 0x30000
	s_addc_u32 s57, s39, 0
	s_barrier
	ds_read_b64_tr_b16 v[208:209], v133 offset:0
	ds_read_b64_tr_b16 v[210:211], v133 offset:4096
	ds_read_b64_tr_b16 v[212:213], v133 offset:16384
	ds_read_b64_tr_b16 v[214:215], v133 offset:20480
	ds_read_b64_tr_b16 v[216:217], v133 offset:32768
	ds_read_b64_tr_b16 v[218:219], v133 offset:36864
	ds_read_b64_tr_b16 v[220:221], v133 offset:49152
	ds_read_b64_tr_b16 v[222:223], v133 offset:53248
	ds_read_b64_tr_b16 v[224:225], v134 offset:0
	ds_read_b64_tr_b16 v[226:227], v134 offset:4096
	ds_read_b64_tr_b16 v[228:229], v134 offset:16384
	ds_read_b64_tr_b16 v[230:231], v134 offset:20480
	ds_read_b64_tr_b16 v[232:233], v134 offset:32768
	ds_read_b64_tr_b16 v[234:235], v134 offset:36864
	ds_read_b64_tr_b16 v[236:237], v134 offset:49152
	ds_read_b64_tr_b16 v[238:239], v134 offset:53248
	s_waitcnt vmcnt(0) lgkmcnt(0)
	v_mfma_f32_32x32x16_bf16 v[112:127], v[208:211], v[8:11], 0
	v_mfma_f32_32x32x16_bf16 v[112:127], v[212:215], v[12:15], v[112:127]
	s_nop 7
	s_nop 7
	v_permlane32_swap_b32 v144, v146
	v_permlane32_swap_b32 v145, v147
	v_permlane32_swap_b32 v148, v150
	v_permlane32_swap_b32 v149, v151
	v_add_f32_e32 v112, v112, v88
	v_add_f32_e32 v113, v113, v88
	v_add_f32_e32 v114, v114, v88
	v_add_f32_e32 v115, v115, v88
	v_add_f32_e32 v116, v116, v88
	v_add_f32_e32 v117, v117, v88
	v_add_f32_e32 v118, v118, v88
	v_add_f32_e32 v119, v119, v88
	v_add_f32_e32 v120, v120, v88
	v_add_f32_e32 v121, v121, v88
	v_add_f32_e32 v122, v122, v88
	v_add_f32_e32 v123, v123, v88
	v_add_f32_e32 v124, v124, v88
	v_add_f32_e32 v125, v125, v88
	v_add_f32_e32 v126, v126, v88
	v_add_f32_e32 v127, v127, v88
	v_lshlrev_b32_e32 v4, 16, v144
	v_mul_f32_e32 v112, v112, v4
	v_and_b32_e32 v4, 0xffff0000, v144
	v_mul_f32_e32 v113, v113, v4
	v_lshlrev_b32_e32 v4, 16, v145
	v_mul_f32_e32 v114, v114, v4
	v_and_b32_e32 v4, 0xffff0000, v145
	v_mul_f32_e32 v115, v115, v4
	v_cvt_pk_bf16_f32 v104, v112, v113
	v_cvt_pk_bf16_f32 v105, v114, v115
	v_lshlrev_b32_e32 v4, 16, v146
	v_mul_f32_e32 v116, v116, v4
	v_and_b32_e32 v4, 0xffff0000, v146
	v_mul_f32_e32 v117, v117, v4
	v_lshlrev_b32_e32 v4, 16, v147
	v_mul_f32_e32 v118, v118, v4
	v_and_b32_e32 v4, 0xffff0000, v147
	v_mul_f32_e32 v119, v119, v4
	v_cvt_pk_bf16_f32 v106, v116, v117
	v_cvt_pk_bf16_f32 v107, v118, v119
	v_lshlrev_b32_e32 v4, 16, v148
	v_mul_f32_e32 v120, v120, v4
	v_and_b32_e32 v4, 0xffff0000, v148
	v_mul_f32_e32 v121, v121, v4
	v_lshlrev_b32_e32 v4, 16, v149
	v_mul_f32_e32 v122, v122, v4
	v_and_b32_e32 v4, 0xffff0000, v149
	v_mul_f32_e32 v123, v123, v4
	v_cvt_pk_bf16_f32 v108, v120, v121
	v_cvt_pk_bf16_f32 v109, v122, v123
	v_lshlrev_b32_e32 v4, 16, v150
	v_mul_f32_e32 v124, v124, v4
	v_and_b32_e32 v4, 0xffff0000, v150
	v_mul_f32_e32 v125, v125, v4
	v_lshlrev_b32_e32 v4, 16, v151
	v_mul_f32_e32 v126, v126, v4
	v_and_b32_e32 v4, 0xffff0000, v151
	v_mul_f32_e32 v127, v127, v4
	v_cvt_pk_bf16_f32 v110, v124, v125
	v_cvt_pk_bf16_f32 v111, v126, v127
	s_nop 1
	v_permlane32_swap_b32 v104, v106
	v_permlane32_swap_b32 v105, v107
	v_permlane32_swap_b32 v108, v110
	v_permlane32_swap_b32 v109, v111
	global_store_dwordx4 v139, v[104:107], s[38:39] offset:0 nt
	global_store_dwordx4 v139, v[108:111], s[38:39] offset:32 nt
	v_mfma_f32_32x32x16_bf16 v[112:127], v[208:211], v[16:19], 0
	v_mfma_f32_32x32x16_bf16 v[112:127], v[212:215], v[20:23], v[112:127]
	v_mfma_f32_32x32x16_bf16 v[112:127], v[216:219], v[24:27], v[112:127]
	v_mfma_f32_32x32x16_bf16 v[112:127], v[220:223], v[28:31], v[112:127]
	s_nop 7
	s_nop 7
	v_permlane32_swap_b32 v160, v162
	v_permlane32_swap_b32 v161, v163
	v_permlane32_swap_b32 v164, v166
	v_permlane32_swap_b32 v165, v167
	v_add_f32_e32 v112, v112, v89
	v_add_f32_e32 v113, v113, v89
	v_add_f32_e32 v114, v114, v89
	v_add_f32_e32 v115, v115, v89
	v_add_f32_e32 v116, v116, v89
	v_add_f32_e32 v117, v117, v89
	v_add_f32_e32 v118, v118, v89
	v_add_f32_e32 v119, v119, v89
	v_add_f32_e32 v120, v120, v89
	v_add_f32_e32 v121, v121, v89
	v_add_f32_e32 v122, v122, v89
	v_add_f32_e32 v123, v123, v89
	v_add_f32_e32 v124, v124, v89
	v_add_f32_e32 v125, v125, v89
	v_add_f32_e32 v126, v126, v89
	v_add_f32_e32 v127, v127, v89
	v_lshlrev_b32_e32 v4, 16, v160
	v_mul_f32_e32 v112, v112, v4
	v_and_b32_e32 v4, 0xffff0000, v160
	v_mul_f32_e32 v113, v113, v4
	v_lshlrev_b32_e32 v4, 16, v161
	v_mul_f32_e32 v114, v114, v4
	v_and_b32_e32 v4, 0xffff0000, v161
	v_mul_f32_e32 v115, v115, v4
	v_cvt_pk_bf16_f32 v104, v112, v113
	v_cvt_pk_bf16_f32 v105, v114, v115
	v_lshlrev_b32_e32 v4, 16, v162
	v_mul_f32_e32 v116, v116, v4
	v_and_b32_e32 v4, 0xffff0000, v162
	v_mul_f32_e32 v117, v117, v4
	v_lshlrev_b32_e32 v4, 16, v163
	v_mul_f32_e32 v118, v118, v4
	v_and_b32_e32 v4, 0xffff0000, v163
	v_mul_f32_e32 v119, v119, v4
	v_cvt_pk_bf16_f32 v106, v116, v117
	v_cvt_pk_bf16_f32 v107, v118, v119
	v_lshlrev_b32_e32 v4, 16, v164
	v_mul_f32_e32 v120, v120, v4
	v_and_b32_e32 v4, 0xffff0000, v164
	v_mul_f32_e32 v121, v121, v4
	v_lshlrev_b32_e32 v4, 16, v165
	v_mul_f32_e32 v122, v122, v4
	v_and_b32_e32 v4, 0xffff0000, v165
	v_mul_f32_e32 v123, v123, v4
	v_cvt_pk_bf16_f32 v108, v120, v121
	v_cvt_pk_bf16_f32 v109, v122, v123
	v_lshlrev_b32_e32 v4, 16, v166
	v_mul_f32_e32 v124, v124, v4
	v_and_b32_e32 v4, 0xffff0000, v166
	v_mul_f32_e32 v125, v125, v4
	v_lshlrev_b32_e32 v4, 16, v167
	v_mul_f32_e32 v126, v126, v4
	v_and_b32_e32 v4, 0xffff0000, v167
	v_mul_f32_e32 v127, v127, v4
	v_cvt_pk_bf16_f32 v110, v124, v125
	v_cvt_pk_bf16_f32 v111, v126, v127
	s_nop 1
	v_permlane32_swap_b32 v104, v106
	v_permlane32_swap_b32 v105, v107
	v_permlane32_swap_b32 v108, v110
	v_permlane32_swap_b32 v109, v111
	global_store_dwordx4 v139, v[104:107], s[46:47] offset:0 nt
	global_store_dwordx4 v139, v[108:111], s[46:47] offset:32 nt
	v_mfma_f32_32x32x16_bf16 v[112:127], v[208:211], v[32:35], 0
	v_mfma_f32_32x32x16_bf16 v[112:127], v[212:215], v[36:39], v[112:127]
	v_mfma_f32_32x32x16_bf16 v[112:127], v[216:219], v[40:43], v[112:127]
	v_mfma_f32_32x32x16_bf16 v[112:127], v[220:223], v[44:47], v[112:127]
	v_mfma_f32_32x32x16_bf16 v[112:127], v[224:227], v[48:51], v[112:127]
	v_mfma_f32_32x32x16_bf16 v[112:127], v[228:231], v[52:55], v[112:127]
	s_nop 7
	s_nop 7
	v_permlane32_swap_b32 v176, v178
	v_permlane32_swap_b32 v177, v179
	v_permlane32_swap_b32 v184, v186
	v_permlane32_swap_b32 v185, v187
	v_add_f32_e32 v112, v112, v90
	v_add_f32_e32 v113, v113, v90
	v_add_f32_e32 v114, v114, v90
	v_add_f32_e32 v115, v115, v90
	v_add_f32_e32 v116, v116, v90
	v_add_f32_e32 v117, v117, v90
	v_add_f32_e32 v118, v118, v90
	v_add_f32_e32 v119, v119, v90
	v_add_f32_e32 v120, v120, v90
	v_add_f32_e32 v121, v121, v90
	v_add_f32_e32 v122, v122, v90
	v_add_f32_e32 v123, v123, v90
	v_add_f32_e32 v124, v124, v90
	v_add_f32_e32 v125, v125, v90
	v_add_f32_e32 v126, v126, v90
	v_add_f32_e32 v127, v127, v90
	v_lshlrev_b32_e32 v4, 16, v176
	v_mul_f32_e32 v112, v112, v4
	v_and_b32_e32 v4, 0xffff0000, v176
	v_mul_f32_e32 v113, v113, v4
	v_lshlrev_b32_e32 v4, 16, v177
	v_mul_f32_e32 v114, v114, v4
	v_and_b32_e32 v4, 0xffff0000, v177
	v_mul_f32_e32 v115, v115, v4
	v_cvt_pk_bf16_f32 v104, v112, v113
	v_cvt_pk_bf16_f32 v105, v114, v115
	v_lshlrev_b32_e32 v4, 16, v178
	v_mul_f32_e32 v116, v116, v4
	v_and_b32_e32 v4, 0xffff0000, v178
	v_mul_f32_e32 v117, v117, v4
	v_lshlrev_b32_e32 v4, 16, v179
	v_mul_f32_e32 v118, v118, v4
	v_and_b32_e32 v4, 0xffff0000, v179
	v_mul_f32_e32 v119, v119, v4
	v_cvt_pk_bf16_f32 v106, v116, v117
	v_cvt_pk_bf16_f32 v107, v118, v119
	v_lshlrev_b32_e32 v4, 16, v184
	v_mul_f32_e32 v120, v120, v4
	v_and_b32_e32 v4, 0xffff0000, v184
	v_mul_f32_e32 v121, v121, v4
	v_lshlrev_b32_e32 v4, 16, v185
	v_mul_f32_e32 v122, v122, v4
	v_and_b32_e32 v4, 0xffff0000, v185
	v_mul_f32_e32 v123, v123, v4
	v_cvt_pk_bf16_f32 v108, v120, v121
	v_cvt_pk_bf16_f32 v109, v122, v123
	v_lshlrev_b32_e32 v4, 16, v186
	v_mul_f32_e32 v124, v124, v4
	v_and_b32_e32 v4, 0xffff0000, v186
	v_mul_f32_e32 v125, v125, v4
	v_lshlrev_b32_e32 v4, 16, v187
	v_mul_f32_e32 v126, v126, v4
	v_and_b32_e32 v4, 0xffff0000, v187
	v_mul_f32_e32 v127, v127, v4
	v_cvt_pk_bf16_f32 v110, v124, v125
	v_cvt_pk_bf16_f32 v111, v126, v127
	s_nop 1
	v_permlane32_swap_b32 v104, v106
	v_permlane32_swap_b32 v105, v107
	v_permlane32_swap_b32 v108, v110
	v_permlane32_swap_b32 v109, v111
	global_store_dwordx4 v139, v[104:107], s[54:55] offset:0 nt
	global_store_dwordx4 v139, v[108:111], s[54:55] offset:32 nt
	v_mfma_f32_32x32x16_bf16 v[112:127], v[208:211], v[56:59], 0
	v_mfma_f32_32x32x16_bf16 v[112:127], v[212:215], v[60:63], v[112:127]
	v_mfma_f32_32x32x16_bf16 v[112:127], v[216:219], v[64:67], v[112:127]
	v_mfma_f32_32x32x16_bf16 v[112:127], v[220:223], v[68:71], v[112:127]
	v_mfma_f32_32x32x16_bf16 v[112:127], v[224:227], v[72:75], v[112:127]
	v_mfma_f32_32x32x16_bf16 v[112:127], v[228:231], v[76:79], v[112:127]
	v_mfma_f32_32x32x16_bf16 v[112:127], v[232:235], v[80:83], v[112:127]
	v_mfma_f32_32x32x16_bf16 v[112:127], v[236:239], v[84:87], v[112:127]
	s_nop 7
	s_nop 7
	v_permlane32_swap_b32 v196, v198
	v_permlane32_swap_b32 v197, v199
	v_permlane32_swap_b32 v200, v202
	v_permlane32_swap_b32 v201, v203
	v_add_f32_e32 v112, v112, v91
	v_add_f32_e32 v113, v113, v91
	v_add_f32_e32 v114, v114, v91
	v_add_f32_e32 v115, v115, v91
	v_add_f32_e32 v116, v116, v91
	v_add_f32_e32 v117, v117, v91
	v_add_f32_e32 v118, v118, v91
	v_add_f32_e32 v119, v119, v91
	v_add_f32_e32 v120, v120, v91
	v_add_f32_e32 v121, v121, v91
	v_add_f32_e32 v122, v122, v91
	v_add_f32_e32 v123, v123, v91
	v_add_f32_e32 v124, v124, v91
	v_add_f32_e32 v125, v125, v91
	v_add_f32_e32 v126, v126, v91
	v_add_f32_e32 v127, v127, v91
	v_lshlrev_b32_e32 v4, 16, v196
	v_mul_f32_e32 v112, v112, v4
	v_and_b32_e32 v4, 0xffff0000, v196
	v_mul_f32_e32 v113, v113, v4
	v_lshlrev_b32_e32 v4, 16, v197
	v_mul_f32_e32 v114, v114, v4
	v_and_b32_e32 v4, 0xffff0000, v197
	v_mul_f32_e32 v115, v115, v4
	v_cvt_pk_bf16_f32 v104, v112, v113
	v_cvt_pk_bf16_f32 v105, v114, v115
	v_lshlrev_b32_e32 v4, 16, v198
	v_mul_f32_e32 v116, v116, v4
	v_and_b32_e32 v4, 0xffff0000, v198
	v_mul_f32_e32 v117, v117, v4
	v_lshlrev_b32_e32 v4, 16, v199
	v_mul_f32_e32 v118, v118, v4
	v_and_b32_e32 v4, 0xffff0000, v199
	v_mul_f32_e32 v119, v119, v4
	v_cvt_pk_bf16_f32 v106, v116, v117
	v_cvt_pk_bf16_f32 v107, v118, v119
	v_lshlrev_b32_e32 v4, 16, v200
	v_mul_f32_e32 v120, v120, v4
	v_and_b32_e32 v4, 0xffff0000, v200
	v_mul_f32_e32 v121, v121, v4
	v_lshlrev_b32_e32 v4, 16, v201
	v_mul_f32_e32 v122, v122, v4
	v_and_b32_e32 v4, 0xffff0000, v201
	v_mul_f32_e32 v123, v123, v4
	v_cvt_pk_bf16_f32 v108, v120, v121
	v_cvt_pk_bf16_f32 v109, v122, v123
	v_lshlrev_b32_e32 v4, 16, v202
	v_mul_f32_e32 v124, v124, v4
	v_and_b32_e32 v4, 0xffff0000, v202
	v_mul_f32_e32 v125, v125, v4
	v_lshlrev_b32_e32 v4, 16, v203
	v_mul_f32_e32 v126, v126, v4
	v_and_b32_e32 v4, 0xffff0000, v203
	v_mul_f32_e32 v127, v127, v4
	v_cvt_pk_bf16_f32 v110, v124, v125
	v_cvt_pk_bf16_f32 v111, v126, v127
	s_nop 1
	v_permlane32_swap_b32 v104, v106
	v_permlane32_swap_b32 v105, v107
	v_permlane32_swap_b32 v108, v110
	v_permlane32_swap_b32 v109, v111
	global_store_dwordx4 v139, v[104:107], s[56:57] offset:0 nt
	global_store_dwordx4 v139, v[108:111], s[56:57] offset:32 nt
	ds_read_b64_tr_b16 v[208:209], v135 offset:0
	ds_read_b64_tr_b16 v[210:211], v135 offset:4096
	ds_read_b64_tr_b16 v[212:213], v135 offset:16384
	ds_read_b64_tr_b16 v[214:215], v135 offset:20480
	ds_read_b64_tr_b16 v[216:217], v135 offset:32768
	ds_read_b64_tr_b16 v[218:219], v135 offset:36864
	ds_read_b64_tr_b16 v[220:221], v135 offset:49152
	ds_read_b64_tr_b16 v[222:223], v135 offset:53248
	ds_read_b64_tr_b16 v[224:225], v136 offset:0
	ds_read_b64_tr_b16 v[226:227], v136 offset:4096
	ds_read_b64_tr_b16 v[228:229], v136 offset:16384
	ds_read_b64_tr_b16 v[230:231], v136 offset:20480
	ds_read_b64_tr_b16 v[232:233], v136 offset:32768
	ds_read_b64_tr_b16 v[234:235], v136 offset:36864
	ds_read_b64_tr_b16 v[236:237], v136 offset:49152
	ds_read_b64_tr_b16 v[238:239], v136 offset:53248
	s_waitcnt vmcnt(0) lgkmcnt(0)
	v_mfma_f32_32x32x16_bf16 v[112:127], v[208:211], v[8:11], 0
	v_mfma_f32_32x32x16_bf16 v[112:127], v[212:215], v[12:15], v[112:127]
	s_nop 7
	s_nop 7
	v_permlane32_swap_b32 v152, v154
	v_permlane32_swap_b32 v153, v155
	v_permlane32_swap_b32 v156, v158
	v_permlane32_swap_b32 v157, v159
	v_add_f32_e32 v112, v112, v88
	v_add_f32_e32 v113, v113, v88
	v_add_f32_e32 v114, v114, v88
	v_add_f32_e32 v115, v115, v88
	v_add_f32_e32 v116, v116, v88
	v_add_f32_e32 v117, v117, v88
	v_add_f32_e32 v118, v118, v88
	v_add_f32_e32 v119, v119, v88
	v_add_f32_e32 v120, v120, v88
	v_add_f32_e32 v121, v121, v88
	v_add_f32_e32 v122, v122, v88
	v_add_f32_e32 v123, v123, v88
	v_add_f32_e32 v124, v124, v88
	v_add_f32_e32 v125, v125, v88
	v_add_f32_e32 v126, v126, v88
	v_add_f32_e32 v127, v127, v88
	v_lshlrev_b32_e32 v4, 16, v152
	v_mul_f32_e32 v112, v112, v4
	v_and_b32_e32 v4, 0xffff0000, v152
	v_mul_f32_e32 v113, v113, v4
	v_lshlrev_b32_e32 v4, 16, v153
	v_mul_f32_e32 v114, v114, v4
	v_and_b32_e32 v4, 0xffff0000, v153
	v_mul_f32_e32 v115, v115, v4
	v_cvt_pk_bf16_f32 v104, v112, v113
	v_cvt_pk_bf16_f32 v105, v114, v115
	v_lshlrev_b32_e32 v4, 16, v154
	v_mul_f32_e32 v116, v116, v4
	v_and_b32_e32 v4, 0xffff0000, v154
	v_mul_f32_e32 v117, v117, v4
	v_lshlrev_b32_e32 v4, 16, v155
	v_mul_f32_e32 v118, v118, v4
	v_and_b32_e32 v4, 0xffff0000, v155
	v_mul_f32_e32 v119, v119, v4
	v_cvt_pk_bf16_f32 v106, v116, v117
	v_cvt_pk_bf16_f32 v107, v118, v119
	v_lshlrev_b32_e32 v4, 16, v156
	v_mul_f32_e32 v120, v120, v4
	v_and_b32_e32 v4, 0xffff0000, v156
	v_mul_f32_e32 v121, v121, v4
	v_lshlrev_b32_e32 v4, 16, v157
	v_mul_f32_e32 v122, v122, v4
	v_and_b32_e32 v4, 0xffff0000, v157
	v_mul_f32_e32 v123, v123, v4
	v_cvt_pk_bf16_f32 v108, v120, v121
	v_cvt_pk_bf16_f32 v109, v122, v123
	v_lshlrev_b32_e32 v4, 16, v158
	v_mul_f32_e32 v124, v124, v4
	v_and_b32_e32 v4, 0xffff0000, v158
	v_mul_f32_e32 v125, v125, v4
	v_lshlrev_b32_e32 v4, 16, v159
	v_mul_f32_e32 v126, v126, v4
	v_and_b32_e32 v4, 0xffff0000, v159
	v_mul_f32_e32 v127, v127, v4
	v_cvt_pk_bf16_f32 v110, v124, v125
	v_cvt_pk_bf16_f32 v111, v126, v127
	s_nop 1
	v_permlane32_swap_b32 v104, v106
	v_permlane32_swap_b32 v105, v107
	v_permlane32_swap_b32 v108, v110
	v_permlane32_swap_b32 v109, v111
	global_store_dwordx4 v139, v[104:107], s[38:39] offset:64 nt
	global_store_dwordx4 v139, v[108:111], s[38:39] offset:96 nt
	v_mfma_f32_32x32x16_bf16 v[112:127], v[208:211], v[16:19], 0
	v_mfma_f32_32x32x16_bf16 v[112:127], v[212:215], v[20:23], v[112:127]
	v_mfma_f32_32x32x16_bf16 v[112:127], v[216:219], v[24:27], v[112:127]
	v_mfma_f32_32x32x16_bf16 v[112:127], v[220:223], v[28:31], v[112:127]
	s_nop 7
	s_nop 7
	v_permlane32_swap_b32 v168, v170
	v_permlane32_swap_b32 v169, v171
	v_permlane32_swap_b32 v172, v174
	v_permlane32_swap_b32 v173, v175
	v_add_f32_e32 v112, v112, v89
	v_add_f32_e32 v113, v113, v89
	v_add_f32_e32 v114, v114, v89
	v_add_f32_e32 v115, v115, v89
	v_add_f32_e32 v116, v116, v89
	v_add_f32_e32 v117, v117, v89
	v_add_f32_e32 v118, v118, v89
	v_add_f32_e32 v119, v119, v89
	v_add_f32_e32 v120, v120, v89
	v_add_f32_e32 v121, v121, v89
	v_add_f32_e32 v122, v122, v89
	v_add_f32_e32 v123, v123, v89
	v_add_f32_e32 v124, v124, v89
	v_add_f32_e32 v125, v125, v89
	v_add_f32_e32 v126, v126, v89
	v_add_f32_e32 v127, v127, v89
	v_lshlrev_b32_e32 v4, 16, v168
	v_mul_f32_e32 v112, v112, v4
	v_and_b32_e32 v4, 0xffff0000, v168
	v_mul_f32_e32 v113, v113, v4
	v_lshlrev_b32_e32 v4, 16, v169
	v_mul_f32_e32 v114, v114, v4
	v_and_b32_e32 v4, 0xffff0000, v169
	v_mul_f32_e32 v115, v115, v4
	v_cvt_pk_bf16_f32 v104, v112, v113
	v_cvt_pk_bf16_f32 v105, v114, v115
	v_lshlrev_b32_e32 v4, 16, v170
	v_mul_f32_e32 v116, v116, v4
	v_and_b32_e32 v4, 0xffff0000, v170
	v_mul_f32_e32 v117, v117, v4
	v_lshlrev_b32_e32 v4, 16, v171
	v_mul_f32_e32 v118, v118, v4
	v_and_b32_e32 v4, 0xffff0000, v171
	v_mul_f32_e32 v119, v119, v4
	v_cvt_pk_bf16_f32 v106, v116, v117
	v_cvt_pk_bf16_f32 v107, v118, v119
	v_lshlrev_b32_e32 v4, 16, v172
	v_mul_f32_e32 v120, v120, v4
	v_and_b32_e32 v4, 0xffff0000, v172
	v_mul_f32_e32 v121, v121, v4
	v_lshlrev_b32_e32 v4, 16, v173
	v_mul_f32_e32 v122, v122, v4
	v_and_b32_e32 v4, 0xffff0000, v173
	v_mul_f32_e32 v123, v123, v4
	v_cvt_pk_bf16_f32 v108, v120, v121
	v_cvt_pk_bf16_f32 v109, v122, v123
	v_lshlrev_b32_e32 v4, 16, v174
	v_mul_f32_e32 v124, v124, v4
	v_and_b32_e32 v4, 0xffff0000, v174
	v_mul_f32_e32 v125, v125, v4
	v_lshlrev_b32_e32 v4, 16, v175
	v_mul_f32_e32 v126, v126, v4
	v_and_b32_e32 v4, 0xffff0000, v175
	v_mul_f32_e32 v127, v127, v4
	v_cvt_pk_bf16_f32 v110, v124, v125
	v_cvt_pk_bf16_f32 v111, v126, v127
	s_nop 1
	v_permlane32_swap_b32 v104, v106
	v_permlane32_swap_b32 v105, v107
	v_permlane32_swap_b32 v108, v110
	v_permlane32_swap_b32 v109, v111
	global_store_dwordx4 v139, v[104:107], s[46:47] offset:64 nt
	global_store_dwordx4 v139, v[108:111], s[46:47] offset:96 nt
	v_mfma_f32_32x32x16_bf16 v[112:127], v[208:211], v[32:35], 0
	v_mfma_f32_32x32x16_bf16 v[112:127], v[212:215], v[36:39], v[112:127]
	v_mfma_f32_32x32x16_bf16 v[112:127], v[216:219], v[40:43], v[112:127]
	v_mfma_f32_32x32x16_bf16 v[112:127], v[220:223], v[44:47], v[112:127]
	v_mfma_f32_32x32x16_bf16 v[112:127], v[224:227], v[48:51], v[112:127]
	v_mfma_f32_32x32x16_bf16 v[112:127], v[228:231], v[52:55], v[112:127]
	s_nop 7
	s_nop 7
	v_permlane32_swap_b32 v188, v190
	v_permlane32_swap_b32 v189, v191
	v_permlane32_swap_b32 v192, v194
	v_permlane32_swap_b32 v193, v195
	v_add_f32_e32 v112, v112, v90
	v_add_f32_e32 v113, v113, v90
	v_add_f32_e32 v114, v114, v90
	v_add_f32_e32 v115, v115, v90
	v_add_f32_e32 v116, v116, v90
	v_add_f32_e32 v117, v117, v90
	v_add_f32_e32 v118, v118, v90
	v_add_f32_e32 v119, v119, v90
	v_add_f32_e32 v120, v120, v90
	v_add_f32_e32 v121, v121, v90
	v_add_f32_e32 v122, v122, v90
	v_add_f32_e32 v123, v123, v90
	v_add_f32_e32 v124, v124, v90
	v_add_f32_e32 v125, v125, v90
	v_add_f32_e32 v126, v126, v90
	v_add_f32_e32 v127, v127, v90
	v_lshlrev_b32_e32 v4, 16, v188
	v_mul_f32_e32 v112, v112, v4
	v_and_b32_e32 v4, 0xffff0000, v188
	v_mul_f32_e32 v113, v113, v4
	v_lshlrev_b32_e32 v4, 16, v189
	v_mul_f32_e32 v114, v114, v4
	v_and_b32_e32 v4, 0xffff0000, v189
	v_mul_f32_e32 v115, v115, v4
	v_cvt_pk_bf16_f32 v104, v112, v113
	v_cvt_pk_bf16_f32 v105, v114, v115
	v_lshlrev_b32_e32 v4, 16, v190
	v_mul_f32_e32 v116, v116, v4
	v_and_b32_e32 v4, 0xffff0000, v190
	v_mul_f32_e32 v117, v117, v4
	v_lshlrev_b32_e32 v4, 16, v191
	v_mul_f32_e32 v118, v118, v4
	v_and_b32_e32 v4, 0xffff0000, v191
	v_mul_f32_e32 v119, v119, v4
	v_cvt_pk_bf16_f32 v106, v116, v117
	v_cvt_pk_bf16_f32 v107, v118, v119
	v_lshlrev_b32_e32 v4, 16, v192
	v_mul_f32_e32 v120, v120, v4
	v_and_b32_e32 v4, 0xffff0000, v192
	v_mul_f32_e32 v121, v121, v4
	v_lshlrev_b32_e32 v4, 16, v193
	v_mul_f32_e32 v122, v122, v4
	v_and_b32_e32 v4, 0xffff0000, v193
	v_mul_f32_e32 v123, v123, v4
	v_cvt_pk_bf16_f32 v108, v120, v121
	v_cvt_pk_bf16_f32 v109, v122, v123
	v_lshlrev_b32_e32 v4, 16, v194
	v_mul_f32_e32 v124, v124, v4
	v_and_b32_e32 v4, 0xffff0000, v194
	v_mul_f32_e32 v125, v125, v4
	v_lshlrev_b32_e32 v4, 16, v195
	v_mul_f32_e32 v126, v126, v4
	v_and_b32_e32 v4, 0xffff0000, v195
	v_mul_f32_e32 v127, v127, v4
	v_cvt_pk_bf16_f32 v110, v124, v125
	v_cvt_pk_bf16_f32 v111, v126, v127
	s_nop 1
	v_permlane32_swap_b32 v104, v106
	v_permlane32_swap_b32 v105, v107
	v_permlane32_swap_b32 v108, v110
	v_permlane32_swap_b32 v109, v111
	global_store_dwordx4 v139, v[104:107], s[54:55] offset:64 nt
	global_store_dwordx4 v139, v[108:111], s[54:55] offset:96 nt
	v_mfma_f32_32x32x16_bf16 v[112:127], v[208:211], v[56:59], 0
	v_mfma_f32_32x32x16_bf16 v[112:127], v[212:215], v[60:63], v[112:127]
	v_mfma_f32_32x32x16_bf16 v[112:127], v[216:219], v[64:67], v[112:127]
	v_mfma_f32_32x32x16_bf16 v[112:127], v[220:223], v[68:71], v[112:127]
	v_mfma_f32_32x32x16_bf16 v[112:127], v[224:227], v[72:75], v[112:127]
	v_mfma_f32_32x32x16_bf16 v[112:127], v[228:231], v[76:79], v[112:127]
	v_mfma_f32_32x32x16_bf16 v[112:127], v[232:235], v[80:83], v[112:127]
	v_mfma_f32_32x32x16_bf16 v[112:127], v[236:239], v[84:87], v[112:127]
	s_nop 7
	s_nop 7
	v_permlane32_swap_b32 v204, v206
	v_permlane32_swap_b32 v205, v207
	v_permlane32_swap_b32 v240, v242
	v_permlane32_swap_b32 v241, v243
	v_add_f32_e32 v112, v112, v91
	v_add_f32_e32 v113, v113, v91
	v_add_f32_e32 v114, v114, v91
	v_add_f32_e32 v115, v115, v91
	v_add_f32_e32 v116, v116, v91
	v_add_f32_e32 v117, v117, v91
	v_add_f32_e32 v118, v118, v91
	v_add_f32_e32 v119, v119, v91
	v_add_f32_e32 v120, v120, v91
	v_add_f32_e32 v121, v121, v91
	v_add_f32_e32 v122, v122, v91
	v_add_f32_e32 v123, v123, v91
	v_add_f32_e32 v124, v124, v91
	v_add_f32_e32 v125, v125, v91
	v_add_f32_e32 v126, v126, v91
	v_add_f32_e32 v127, v127, v91
	v_lshlrev_b32_e32 v4, 16, v204
	v_mul_f32_e32 v112, v112, v4
	v_and_b32_e32 v4, 0xffff0000, v204
	v_mul_f32_e32 v113, v113, v4
	v_lshlrev_b32_e32 v4, 16, v205
	v_mul_f32_e32 v114, v114, v4
	v_and_b32_e32 v4, 0xffff0000, v205
	v_mul_f32_e32 v115, v115, v4
	v_cvt_pk_bf16_f32 v104, v112, v113
	v_cvt_pk_bf16_f32 v105, v114, v115
	v_lshlrev_b32_e32 v4, 16, v206
	v_mul_f32_e32 v116, v116, v4
	v_and_b32_e32 v4, 0xffff0000, v206
	v_mul_f32_e32 v117, v117, v4
	v_lshlrev_b32_e32 v4, 16, v207
	v_mul_f32_e32 v118, v118, v4
	v_and_b32_e32 v4, 0xffff0000, v207
	v_mul_f32_e32 v119, v119, v4
	v_cvt_pk_bf16_f32 v106, v116, v117
	v_cvt_pk_bf16_f32 v107, v118, v119
	v_lshlrev_b32_e32 v4, 16, v240
	v_mul_f32_e32 v120, v120, v4
	v_and_b32_e32 v4, 0xffff0000, v240
	v_mul_f32_e32 v121, v121, v4
	v_lshlrev_b32_e32 v4, 16, v241
	v_mul_f32_e32 v122, v122, v4
	v_and_b32_e32 v4, 0xffff0000, v241
	v_mul_f32_e32 v123, v123, v4
	v_cvt_pk_bf16_f32 v108, v120, v121
	v_cvt_pk_bf16_f32 v109, v122, v123
	v_lshlrev_b32_e32 v4, 16, v242
	v_mul_f32_e32 v124, v124, v4
	v_and_b32_e32 v4, 0xffff0000, v242
	v_mul_f32_e32 v125, v125, v4
	v_lshlrev_b32_e32 v4, 16, v243
	v_mul_f32_e32 v126, v126, v4
	v_and_b32_e32 v4, 0xffff0000, v243
	v_mul_f32_e32 v127, v127, v4
	v_cvt_pk_bf16_f32 v110, v124, v125
	v_cvt_pk_bf16_f32 v111, v126, v127
	s_nop 1
	v_permlane32_swap_b32 v104, v106
	v_permlane32_swap_b32 v105, v107
	v_permlane32_swap_b32 v108, v110
	v_permlane32_swap_b32 v109, v111
	global_store_dwordx4 v139, v[104:107], s[56:57] offset:64 nt
	global_store_dwordx4 v139, v[108:111], s[56:57] offset:96 nt
	s_add_i32 s1, s1, s66
	s_cmp_lt_i32 s1, 0x100
	s_cbranch_scc0 .Lgm_done
	s_barrier
	s_branch .Lgm_loop

.LBB0_1502:
	s_or_b64 exec, exec, s[6:7]
	v_cvt_f32_u32_e32 v4, v2
	s_waitcnt vmcnt(0)
	v_readfirstlane_b32 s4, v3
	v_sub_u32_e32 v3, 0, v2
	v_rcp_iflag_f32_e32 v4, v4
	v_add_u32_e32 v5, s4, v1
	v_mul_f32_e32 v4, 0x4f7ffffe, v4
	v_cvt_u32_f32_e32 v4, v4
	v_mul_lo_u32 v1, v3, v4
	v_mul_hi_u32 v1, v4, v1
	v_add_u32_e32 v1, v4, v1
	v_mul_hi_u32 v1, v5, v1
	v_mul_lo_u32 v3, v1, v2
	v_sub_u32_e32 v3, v5, v3
	v_add_u32_e32 v4, 1, v1
	v_cmp_ge_u32_e32 vcc, v3, v2
	s_nop 1
	v_cndmask_b32_e32 v1, v1, v4, vcc
	v_sub_u32_e32 v4, v3, v2
	v_cndmask_b32_e32 v3, v3, v4, vcc
	v_add_u32_e32 v4, 1, v1
	v_cmp_ge_u32_e32 vcc, v3, v2
	v_add_u32_e32 v3, 1, v5
	s_nop 0
	v_cndmask_b32_e32 v1, v1, v4, vcc
	v_mul_lo_u32 v4, v2, v1
	v_add_u32_e32 v2, v4, v2
	v_cmp_ne_u32_e32 vcc, v3, v2
	s_and_saveexec_b64 s[4:5], vcc
	s_xor_b64 s[4:5], exec, s[4:5]
	s_cbranch_execz .LBB0_1516
	s_waitcnt lgkmcnt(0)
	v_mov_b32_e32 v0, 0x83500
	global_load_dword v0, v0, s[64:65] sc1
	s_add_u32 s10, s64, 0x83500
	s_addc_u32 s11, s65, 0
	s_waitcnt vmcnt(0)
	v_cmp_eq_u32_e32 vcc, v0, v1
	s_and_saveexec_b64 s[6:7], vcc
	s_cbranch_execz .LBB0_1515
	s_add_u32 s8, s64, 0x80200
	s_addc_u32 s9, s65, 0
	s_mov_b32 s22, 1
	s_mov_b64 s[12:13], 0
	v_mov_b32_e32 v0, 0
	s_branch .LBB0_1506
